# scan: hand-scheduled consumer loop + bonus sums distributed over the 4 row-quarter workgroups
# speedup vs baseline: 1.0398x; 1.0398x over previous
.LBB0_1344:
	s_and_b32 s17, s61, 32
	s_mulk_i32 s17, 0x540
	s_add_i32 s56, s91, s17
	v_lshl_add_u32 v67, v77, 2, s56
	v_lshl_add_u32 v85, v60, 2, s56
	ds_read_b128 v[4:7], v67
	ds_read_b128 v[12:15], v67 offset:512
	ds_read_b128 v[16:19], v67 offset:768
	ds_read_b128 v[8:11], v67 offset:256
	ds_read_b128 v[20:23], v67 offset:1024
	ds_read_b32 v74, v85 offset:1280
	ds_read_b128 v[24:27], v67 offset:1344
	ds_read_b128 v[32:35], v67 offset:1856
	ds_read_b128 v[36:39], v67 offset:2112
	ds_read_b128 v[28:31], v67 offset:1600
	ds_read_b128 v[40:43], v67 offset:2368
	ds_read_b32 v76, v85 offset:2624
	s_ashr_i32 s17, s16, 31
	s_lshl_b64 s[16:17], s[16:17], 11
	v_lshl_add_u64 v[72:73], v[68:69], 0, s[16:17]
	v_lshl_add_u64 v[72:73], v[70:71], 1, v[72:73]
	s_waitcnt lgkmcnt(6)
	v_pk_mul_f32 v[86:87], v[12:13], v[74:75] op_sel_hi:[1,0]
	v_pk_mul_f32 v[90:91], v[0:1], v[4:5]
	v_pk_mul_f32 v[88:89], v[14:15], v[74:75] op_sel_hi:[1,0]
	v_pk_fma_f32 v[90:91], v[2:3], v[6:7], v[90:91]
	v_pk_fma_f32 v[86:87], v[0:1], v[16:17], v[86:87]
	ds_read_b128 v[44:47], v67 offset:2688
	v_add_f32_e32 v92, v90, v91
	ds_read_b128 v[52:55], v67 offset:3200
	ds_read_b128 v[56:59], v67 offset:3456
	v_add_f32_dpp v92, v92, v92 quad_perm:[1,0,3,2] row_mask:0xf bank_mask:0xf bound_ctrl:1
	ds_read_b128 v[48:51], v67 offset:2944
	ds_read_b128 v[80:83], v67 offset:3712
	v_add_f32_dpp v92, v92, v92 quad_perm:[2,3,0,1] row_mask:0xf bank_mask:0xf bound_ctrl:1
	ds_read_b32 v78, v85 offset:3968
	s_nop 0
	v_add_f32_dpp v92, v92, v92 row_half_mirror row_mask:0xf bank_mask:0xf bound_ctrl:1
	v_pk_fma_f32 v[88:89], v[2:3], v[18:19], v[88:89]
	s_nop 0
	v_add_f32_dpp v92, v92, v92 row_mirror row_mask:0xf bank_mask:0xf bound_ctrl:1
	v_pk_fma_f32 v[0:1], v[8:9], v[92:93], v[86:87] op_sel_hi:[1,0,1]
	v_pk_fma_f32 v[2:3], v[10:11], v[92:93], v[88:89] op_sel_hi:[1,0,1]
	s_waitcnt lgkmcnt(6)
	v_pk_mul_f32 v[86:87], v[32:33], v[76:77] op_sel_hi:[1,0]
	v_pk_mul_f32 v[90:91], v[0:1], v[24:25]
	v_pk_mul_f32 v[88:89], v[34:35], v[76:77] op_sel_hi:[1,0]
	v_pk_fma_f32 v[90:91], v[2:3], v[26:27], v[90:91]
	v_pk_fma_f32 v[86:87], v[0:1], v[36:37], v[86:87]
	v_pk_mul_f32 v[94:95], v[0:1], v[20:21]
	v_add_f32_e32 v92, v90, v91
	v_pk_fma_f32 v[94:95], v[2:3], v[22:23], v[94:95]
	ds_read_b128 v[4:7], v67 offset:4032
	v_add_f32_dpp v92, v92, v92 quad_perm:[1,0,3,2] row_mask:0xf bank_mask:0xf bound_ctrl:1
	ds_read_b128 v[12:15], v67 offset:4544
	ds_read_b128 v[16:19], v67 offset:4800
	v_add_f32_dpp v92, v92, v92 quad_perm:[2,3,0,1] row_mask:0xf bank_mask:0xf bound_ctrl:1
	ds_read_b128 v[8:11], v67 offset:4288
	ds_read_b128 v[20:23], v67 offset:5056
	v_add_f32_dpp v92, v92, v92 row_half_mirror row_mask:0xf bank_mask:0xf bound_ctrl:1
	ds_read_b32 v74, v85 offset:5312
	v_pk_fma_f32 v[88:89], v[2:3], v[38:39], v[88:89]
	v_add_f32_dpp v92, v92, v92 row_mirror row_mask:0xf bank_mask:0xf bound_ctrl:1
	v_add_f32_e32 v96, v94, v95
	v_pk_fma_f32 v[0:1], v[28:29], v[92:93], v[86:87] op_sel_hi:[1,0,1]
	v_pk_fma_f32 v[2:3], v[30:31], v[92:93], v[88:89] op_sel_hi:[1,0,1]
	s_waitcnt lgkmcnt(6)
	v_pk_mul_f32 v[86:87], v[52:53], v[78:79] op_sel_hi:[1,0]
	v_pk_mul_f32 v[90:91], v[0:1], v[44:45]
	v_pk_mul_f32 v[88:89], v[54:55], v[78:79] op_sel_hi:[1,0]
	v_pk_fma_f32 v[90:91], v[2:3], v[46:47], v[90:91]
	v_pk_fma_f32 v[86:87], v[0:1], v[56:57], v[86:87]
	v_pk_mul_f32 v[94:95], v[0:1], v[40:41]
	v_add_f32_e32 v92, v90, v91
	v_pk_fma_f32 v[94:95], v[2:3], v[42:43], v[94:95]
	ds_read_b128 v[24:27], v67 offset:5376
	v_add_f32_dpp v92, v92, v92 quad_perm:[1,0,3,2] row_mask:0xf bank_mask:0xf bound_ctrl:1
	ds_read_b128 v[32:35], v67 offset:5888
	ds_read_b128 v[36:39], v67 offset:6144
	v_add_f32_dpp v92, v92, v92 quad_perm:[2,3,0,1] row_mask:0xf bank_mask:0xf bound_ctrl:1
	ds_read_b128 v[28:31], v67 offset:5632
	ds_read_b128 v[40:43], v67 offset:6400
	v_add_f32_dpp v92, v92, v92 row_half_mirror row_mask:0xf bank_mask:0xf bound_ctrl:1
	ds_read_b32 v76, v85 offset:6656
	v_pk_fma_f32 v[88:89], v[2:3], v[58:59], v[88:89]
	v_add_f32_dpp v92, v92, v92 row_mirror row_mask:0xf bank_mask:0xf bound_ctrl:1
	v_add_f32_e32 v97, v94, v95
	v_pk_fma_f32 v[0:1], v[48:49], v[92:93], v[86:87] op_sel_hi:[1,0,1]
	v_pk_fma_f32 v[2:3], v[50:51], v[92:93], v[88:89] op_sel_hi:[1,0,1]
	s_waitcnt lgkmcnt(6)
	v_pk_mul_f32 v[86:87], v[12:13], v[74:75] op_sel_hi:[1,0]
	v_pk_mul_f32 v[90:91], v[0:1], v[4:5]
	v_pk_mul_f32 v[88:89], v[14:15], v[74:75] op_sel_hi:[1,0]
	v_pk_fma_f32 v[90:91], v[2:3], v[6:7], v[90:91]
	v_pk_fma_f32 v[86:87], v[0:1], v[16:17], v[86:87]
	v_pk_mul_f32 v[94:95], v[0:1], v[80:81]
	v_add_f32_e32 v92, v90, v91
	v_pk_fma_f32 v[94:95], v[2:3], v[82:83], v[94:95]
	ds_read_b128 v[44:47], v67 offset:6720
	v_add_f32_dpp v92, v92, v92 quad_perm:[1,0,3,2] row_mask:0xf bank_mask:0xf bound_ctrl:1
	ds_read_b128 v[52:55], v67 offset:7232
	ds_read_b128 v[56:59], v67 offset:7488
	v_add_f32_dpp v92, v92, v92 quad_perm:[2,3,0,1] row_mask:0xf bank_mask:0xf bound_ctrl:1
	ds_read_b128 v[48:51], v67 offset:6976
	ds_read_b128 v[80:83], v67 offset:7744
	v_add_f32_dpp v92, v92, v92 row_half_mirror row_mask:0xf bank_mask:0xf bound_ctrl:1
	ds_read_b32 v78, v85 offset:8000
	v_pk_fma_f32 v[88:89], v[2:3], v[18:19], v[88:89]
	v_add_f32_dpp v92, v92, v92 row_mirror row_mask:0xf bank_mask:0xf bound_ctrl:1
	v_add_f32_e32 v98, v94, v95
	v_pk_fma_f32 v[0:1], v[8:9], v[92:93], v[86:87] op_sel_hi:[1,0,1]
	v_pk_fma_f32 v[2:3], v[10:11], v[92:93], v[88:89] op_sel_hi:[1,0,1]
	s_waitcnt lgkmcnt(6)
	v_pk_mul_f32 v[86:87], v[32:33], v[76:77] op_sel_hi:[1,0]
	v_pk_mul_f32 v[90:91], v[0:1], v[24:25]
	v_pk_mul_f32 v[88:89], v[34:35], v[76:77] op_sel_hi:[1,0]
	v_pk_fma_f32 v[90:91], v[2:3], v[26:27], v[90:91]
	v_pk_fma_f32 v[86:87], v[0:1], v[36:37], v[86:87]
	v_pk_mul_f32 v[94:95], v[0:1], v[20:21]
	v_add_f32_e32 v92, v90, v91
	v_pk_fma_f32 v[94:95], v[2:3], v[22:23], v[94:95]
	ds_read_b128 v[4:7], v67 offset:8064
	v_add_f32_dpp v92, v92, v92 quad_perm:[1,0,3,2] row_mask:0xf bank_mask:0xf bound_ctrl:1
	ds_read_b128 v[12:15], v67 offset:8576
	ds_read_b128 v[16:19], v67 offset:8832
	v_add_f32_dpp v92, v92, v92 quad_perm:[2,3,0,1] row_mask:0xf bank_mask:0xf bound_ctrl:1
	ds_read_b128 v[8:11], v67 offset:8320
	ds_read_b128 v[20:23], v67 offset:9088
	v_add_f32_dpp v92, v92, v92 row_half_mirror row_mask:0xf bank_mask:0xf bound_ctrl:1
	ds_read_b32 v74, v85 offset:9344
	v_pk_fma_f32 v[88:89], v[2:3], v[38:39], v[88:89]
	v_add_f32_dpp v92, v92, v92 row_mirror row_mask:0xf bank_mask:0xf bound_ctrl:1
	v_add_f32_e32 v99, v94, v95
	v_cndmask_b32_e64 v100, v98, v96, s[6:7]
	v_pk_fma_f32 v[0:1], v[28:29], v[92:93], v[86:87] op_sel_hi:[1,0,1]
	v_pk_fma_f32 v[2:3], v[30:31], v[92:93], v[88:89] op_sel_hi:[1,0,1]
	v_cndmask_b32_e64 v101, v96, v98, s[6:7]
	v_cndmask_b32_e64 v102, v99, v97, s[6:7]
	v_cndmask_b32_e64 v103, v97, v99, s[6:7]
	s_waitcnt lgkmcnt(6)
	v_pk_mul_f32 v[86:87], v[52:53], v[78:79] op_sel_hi:[1,0]
	v_pk_mul_f32 v[90:91], v[0:1], v[44:45]
	v_pk_mul_f32 v[88:89], v[54:55], v[78:79] op_sel_hi:[1,0]
	v_pk_fma_f32 v[90:91], v[2:3], v[46:47], v[90:91]
	v_pk_fma_f32 v[86:87], v[0:1], v[56:57], v[86:87]
	v_pk_mul_f32 v[94:95], v[0:1], v[40:41]
	v_add_f32_e32 v92, v90, v91
	v_pk_fma_f32 v[94:95], v[2:3], v[42:43], v[94:95]
	ds_read_b128 v[24:27], v67 offset:9408
	v_add_f32_dpp v92, v92, v92 quad_perm:[1,0,3,2] row_mask:0xf bank_mask:0xf bound_ctrl:1
	ds_read_b128 v[32:35], v67 offset:9920
	ds_read_b128 v[36:39], v67 offset:10176
	v_add_f32_dpp v92, v92, v92 quad_perm:[2,3,0,1] row_mask:0xf bank_mask:0xf bound_ctrl:1
	ds_read_b128 v[28:31], v67 offset:9664
	ds_read_b128 v[40:43], v67 offset:10432
	v_add_f32_dpp v92, v92, v92 row_half_mirror row_mask:0xf bank_mask:0xf bound_ctrl:1
	ds_read_b32 v76, v85 offset:10688
	v_pk_fma_f32 v[88:89], v[2:3], v[58:59], v[88:89]
	v_add_f32_dpp v92, v92, v92 row_mirror row_mask:0xf bank_mask:0xf bound_ctrl:1
	v_add_f32_e32 v96, v94, v95
	v_add_f32_dpp v100, v101, v100 quad_perm:[1,0,3,2] row_mask:0xf bank_mask:0xf bound_ctrl:1
	v_pk_fma_f32 v[0:1], v[48:49], v[92:93], v[86:87] op_sel_hi:[1,0,1]
	v_pk_fma_f32 v[2:3], v[50:51], v[92:93], v[88:89] op_sel_hi:[1,0,1]
	v_add_f32_dpp v103, v103, v102 quad_perm:[1,0,3,2] row_mask:0xf bank_mask:0xf bound_ctrl:1
	v_cndmask_b32_e64 v104, v103, v100, s[8:9]
	v_cndmask_b32_e64 v105, v100, v103, s[8:9]
	s_waitcnt lgkmcnt(6)
	v_pk_mul_f32 v[86:87], v[12:13], v[74:75] op_sel_hi:[1,0]
	v_pk_mul_f32 v[90:91], v[0:1], v[4:5]
	v_pk_mul_f32 v[88:89], v[14:15], v[74:75] op_sel_hi:[1,0]
	v_pk_fma_f32 v[90:91], v[2:3], v[6:7], v[90:91]
	v_pk_fma_f32 v[86:87], v[0:1], v[16:17], v[86:87]
	v_pk_mul_f32 v[94:95], v[0:1], v[80:81]
	v_add_f32_e32 v92, v90, v91
	v_pk_fma_f32 v[94:95], v[2:3], v[82:83], v[94:95]
	ds_read_b128 v[44:47], v67 offset:10752
	v_add_f32_dpp v92, v92, v92 quad_perm:[1,0,3,2] row_mask:0xf bank_mask:0xf bound_ctrl:1
	ds_read_b128 v[52:55], v67 offset:11264
	ds_read_b128 v[56:59], v67 offset:11520
	v_add_f32_dpp v92, v92, v92 quad_perm:[2,3,0,1] row_mask:0xf bank_mask:0xf bound_ctrl:1
	ds_read_b128 v[48:51], v67 offset:11008
	ds_read_b128 v[80:83], v67 offset:11776
	v_add_f32_dpp v92, v92, v92 row_half_mirror row_mask:0xf bank_mask:0xf bound_ctrl:1
	ds_read_b32 v78, v85 offset:12032
	v_pk_fma_f32 v[88:89], v[2:3], v[18:19], v[88:89]
	v_add_f32_dpp v92, v92, v92 row_mirror row_mask:0xf bank_mask:0xf bound_ctrl:1
	v_add_f32_e32 v97, v94, v95
	v_add_f32_dpp v105, v105, v104 quad_perm:[2,3,0,1] row_mask:0xf bank_mask:0xf bound_ctrl:1
	v_pk_fma_f32 v[0:1], v[8:9], v[92:93], v[86:87] op_sel_hi:[1,0,1]
	v_pk_fma_f32 v[2:3], v[10:11], v[92:93], v[88:89] op_sel_hi:[1,0,1]
	v_add_f32_dpp v105, v105, v105 row_ror:4 row_mask:0xf bank_mask:0xf bound_ctrl:1
	s_waitcnt lgkmcnt(6)
	v_pk_mul_f32 v[86:87], v[32:33], v[76:77] op_sel_hi:[1,0]
	v_pk_mul_f32 v[90:91], v[0:1], v[24:25]
	v_pk_mul_f32 v[88:89], v[34:35], v[76:77] op_sel_hi:[1,0]
	v_pk_fma_f32 v[90:91], v[2:3], v[26:27], v[90:91]
	v_pk_fma_f32 v[86:87], v[0:1], v[36:37], v[86:87]
	v_pk_mul_f32 v[94:95], v[0:1], v[20:21]
	v_add_f32_e32 v92, v90, v91
	v_pk_fma_f32 v[94:95], v[2:3], v[22:23], v[94:95]
	ds_read_b128 v[4:7], v67 offset:12096
	v_add_f32_dpp v92, v92, v92 quad_perm:[1,0,3,2] row_mask:0xf bank_mask:0xf bound_ctrl:1
	ds_read_b128 v[12:15], v67 offset:12608
	ds_read_b128 v[16:19], v67 offset:12864
	v_add_f32_dpp v92, v92, v92 quad_perm:[2,3,0,1] row_mask:0xf bank_mask:0xf bound_ctrl:1
	ds_read_b128 v[8:11], v67 offset:12352
	ds_read_b128 v[20:23], v67 offset:13120
	v_add_f32_dpp v92, v92, v92 row_half_mirror row_mask:0xf bank_mask:0xf bound_ctrl:1
	ds_read_b32 v74, v85 offset:13376
	v_pk_fma_f32 v[88:89], v[2:3], v[38:39], v[88:89]
	v_add_f32_dpp v92, v92, v92 row_mirror row_mask:0xf bank_mask:0xf bound_ctrl:1
	v_add_f32_e32 v98, v94, v95
	v_mov_b32_dpp v106, v105 row_ror:8 row_mask:0xf bank_mask:0xf bound_ctrl:1
	v_pk_fma_f32 v[0:1], v[28:29], v[92:93], v[86:87] op_sel_hi:[1,0,1]
	v_pk_fma_f32 v[2:3], v[30:31], v[92:93], v[88:89] op_sel_hi:[1,0,1]
	v_add_f32_e32 v107, v105, v106
	v_cvt_pk_bf16_f32 v107, v107, v107
	s_and_saveexec_b64 s[16:17], s[4:5]
	global_store_short v[72:73], v107, off
	s_or_b64 exec, exec, s[16:17]
	v_lshl_add_u64 v[72:73], v[72:73], 0, s[14:15]
	s_waitcnt lgkmcnt(6)
	v_pk_mul_f32 v[86:87], v[52:53], v[78:79] op_sel_hi:[1,0]
	v_pk_mul_f32 v[90:91], v[0:1], v[44:45]
	v_pk_mul_f32 v[88:89], v[54:55], v[78:79] op_sel_hi:[1,0]
	v_pk_fma_f32 v[90:91], v[2:3], v[46:47], v[90:91]
	v_pk_fma_f32 v[86:87], v[0:1], v[56:57], v[86:87]
	v_pk_mul_f32 v[94:95], v[0:1], v[40:41]
	v_add_f32_e32 v92, v90, v91
	v_pk_fma_f32 v[94:95], v[2:3], v[42:43], v[94:95]
	ds_read_b128 v[24:27], v67 offset:13440
	v_add_f32_dpp v92, v92, v92 quad_perm:[1,0,3,2] row_mask:0xf bank_mask:0xf bound_ctrl:1
	ds_read_b128 v[32:35], v67 offset:13952
	ds_read_b128 v[36:39], v67 offset:14208
	v_add_f32_dpp v92, v92, v92 quad_perm:[2,3,0,1] row_mask:0xf bank_mask:0xf bound_ctrl:1
	ds_read_b128 v[28:31], v67 offset:13696
	ds_read_b128 v[40:43], v67 offset:14464
	v_add_f32_dpp v92, v92, v92 row_half_mirror row_mask:0xf bank_mask:0xf bound_ctrl:1
	ds_read_b32 v76, v85 offset:14720
	v_pk_fma_f32 v[88:89], v[2:3], v[58:59], v[88:89]
	v_add_f32_dpp v92, v92, v92 row_mirror row_mask:0xf bank_mask:0xf bound_ctrl:1
	v_add_f32_e32 v99, v94, v95
	v_cndmask_b32_e64 v100, v98, v96, s[6:7]
	v_pk_fma_f32 v[0:1], v[48:49], v[92:93], v[86:87] op_sel_hi:[1,0,1]
	v_pk_fma_f32 v[2:3], v[50:51], v[92:93], v[88:89] op_sel_hi:[1,0,1]
	v_cndmask_b32_e64 v101, v96, v98, s[6:7]
	v_cndmask_b32_e64 v102, v99, v97, s[6:7]
	v_cndmask_b32_e64 v103, v97, v99, s[6:7]
	s_waitcnt lgkmcnt(6)
	v_pk_mul_f32 v[86:87], v[12:13], v[74:75] op_sel_hi:[1,0]
	v_pk_mul_f32 v[90:91], v[0:1], v[4:5]
	v_pk_mul_f32 v[88:89], v[14:15], v[74:75] op_sel_hi:[1,0]
	v_pk_fma_f32 v[90:91], v[2:3], v[6:7], v[90:91]
	v_pk_fma_f32 v[86:87], v[0:1], v[16:17], v[86:87]
	v_pk_mul_f32 v[94:95], v[0:1], v[80:81]
	v_add_f32_e32 v92, v90, v91
	v_pk_fma_f32 v[94:95], v[2:3], v[82:83], v[94:95]
	ds_read_b128 v[44:47], v67 offset:14784
	v_add_f32_dpp v92, v92, v92 quad_perm:[1,0,3,2] row_mask:0xf bank_mask:0xf bound_ctrl:1
	ds_read_b128 v[52:55], v67 offset:15296
	ds_read_b128 v[56:59], v67 offset:15552
	v_add_f32_dpp v92, v92, v92 quad_perm:[2,3,0,1] row_mask:0xf bank_mask:0xf bound_ctrl:1
	ds_read_b128 v[48:51], v67 offset:15040
	ds_read_b128 v[80:83], v67 offset:15808
	v_add_f32_dpp v92, v92, v92 row_half_mirror row_mask:0xf bank_mask:0xf bound_ctrl:1
	ds_read_b32 v78, v85 offset:16064
	v_pk_fma_f32 v[88:89], v[2:3], v[18:19], v[88:89]
	v_add_f32_dpp v92, v92, v92 row_mirror row_mask:0xf bank_mask:0xf bound_ctrl:1
	v_add_f32_e32 v96, v94, v95
	v_add_f32_dpp v100, v101, v100 quad_perm:[1,0,3,2] row_mask:0xf bank_mask:0xf bound_ctrl:1
	v_pk_fma_f32 v[0:1], v[8:9], v[92:93], v[86:87] op_sel_hi:[1,0,1]
	v_pk_fma_f32 v[2:3], v[10:11], v[92:93], v[88:89] op_sel_hi:[1,0,1]
	v_add_f32_dpp v103, v103, v102 quad_perm:[1,0,3,2] row_mask:0xf bank_mask:0xf bound_ctrl:1
	v_cndmask_b32_e64 v104, v103, v100, s[8:9]
	v_cndmask_b32_e64 v105, v100, v103, s[8:9]
	s_waitcnt lgkmcnt(6)
	v_pk_mul_f32 v[86:87], v[32:33], v[76:77] op_sel_hi:[1,0]
	v_pk_mul_f32 v[90:91], v[0:1], v[24:25]
	v_pk_mul_f32 v[88:89], v[34:35], v[76:77] op_sel_hi:[1,0]
	v_pk_fma_f32 v[90:91], v[2:3], v[26:27], v[90:91]
	v_pk_fma_f32 v[86:87], v[0:1], v[36:37], v[86:87]
	v_pk_mul_f32 v[94:95], v[0:1], v[20:21]
	v_add_f32_e32 v92, v90, v91
	v_pk_fma_f32 v[94:95], v[2:3], v[22:23], v[94:95]
	ds_read_b128 v[4:7], v67 offset:16128
	v_add_f32_dpp v92, v92, v92 quad_perm:[1,0,3,2] row_mask:0xf bank_mask:0xf bound_ctrl:1
	ds_read_b128 v[12:15], v67 offset:16640
	ds_read_b128 v[16:19], v67 offset:16896
	v_add_f32_dpp v92, v92, v92 quad_perm:[2,3,0,1] row_mask:0xf bank_mask:0xf bound_ctrl:1
	ds_read_b128 v[8:11], v67 offset:16384
	ds_read_b128 v[20:23], v67 offset:17152
	v_add_f32_dpp v92, v92, v92 row_half_mirror row_mask:0xf bank_mask:0xf bound_ctrl:1
	ds_read_b32 v74, v85 offset:17408
	v_pk_fma_f32 v[88:89], v[2:3], v[38:39], v[88:89]
	v_add_f32_dpp v92, v92, v92 row_mirror row_mask:0xf bank_mask:0xf bound_ctrl:1
	v_add_f32_e32 v97, v94, v95
	v_add_f32_dpp v105, v105, v104 quad_perm:[2,3,0,1] row_mask:0xf bank_mask:0xf bound_ctrl:1
	v_pk_fma_f32 v[0:1], v[28:29], v[92:93], v[86:87] op_sel_hi:[1,0,1]
	v_pk_fma_f32 v[2:3], v[30:31], v[92:93], v[88:89] op_sel_hi:[1,0,1]
	v_add_f32_dpp v105, v105, v105 row_ror:4 row_mask:0xf bank_mask:0xf bound_ctrl:1
	s_waitcnt lgkmcnt(6)
	v_pk_mul_f32 v[86:87], v[52:53], v[78:79] op_sel_hi:[1,0]
	v_pk_mul_f32 v[90:91], v[0:1], v[44:45]
	v_pk_mul_f32 v[88:89], v[54:55], v[78:79] op_sel_hi:[1,0]
	v_pk_fma_f32 v[90:91], v[2:3], v[46:47], v[90:91]
	v_pk_fma_f32 v[86:87], v[0:1], v[56:57], v[86:87]
	v_pk_mul_f32 v[94:95], v[0:1], v[40:41]
	v_add_f32_e32 v92, v90, v91
	v_pk_fma_f32 v[94:95], v[2:3], v[42:43], v[94:95]
	ds_read_b128 v[24:27], v67 offset:17472
	v_add_f32_dpp v92, v92, v92 quad_perm:[1,0,3,2] row_mask:0xf bank_mask:0xf bound_ctrl:1
	ds_read_b128 v[32:35], v67 offset:17984
	ds_read_b128 v[36:39], v67 offset:18240
	v_add_f32_dpp v92, v92, v92 quad_perm:[2,3,0,1] row_mask:0xf bank_mask:0xf bound_ctrl:1
	ds_read_b128 v[28:31], v67 offset:17728
	ds_read_b128 v[40:43], v67 offset:18496
	v_add_f32_dpp v92, v92, v92 row_half_mirror row_mask:0xf bank_mask:0xf bound_ctrl:1
	ds_read_b32 v76, v85 offset:18752
	v_pk_fma_f32 v[88:89], v[2:3], v[58:59], v[88:89]
	v_add_f32_dpp v92, v92, v92 row_mirror row_mask:0xf bank_mask:0xf bound_ctrl:1
	v_add_f32_e32 v98, v94, v95
	v_mov_b32_dpp v106, v105 row_ror:8 row_mask:0xf bank_mask:0xf bound_ctrl:1
	v_pk_fma_f32 v[0:1], v[48:49], v[92:93], v[86:87] op_sel_hi:[1,0,1]
	v_pk_fma_f32 v[2:3], v[50:51], v[92:93], v[88:89] op_sel_hi:[1,0,1]
	v_add_f32_e32 v107, v105, v106
	v_cvt_pk_bf16_f32 v107, v107, v107
	s_and_saveexec_b64 s[16:17], s[4:5]
	global_store_short v[72:73], v107, off
	s_or_b64 exec, exec, s[16:17]
	v_lshl_add_u64 v[72:73], v[72:73], 0, s[14:15]
	s_waitcnt lgkmcnt(6)
	v_pk_mul_f32 v[86:87], v[12:13], v[74:75] op_sel_hi:[1,0]
	v_pk_mul_f32 v[90:91], v[0:1], v[4:5]
	v_pk_mul_f32 v[88:89], v[14:15], v[74:75] op_sel_hi:[1,0]
	v_pk_fma_f32 v[90:91], v[2:3], v[6:7], v[90:91]
	v_pk_fma_f32 v[86:87], v[0:1], v[16:17], v[86:87]
	v_pk_mul_f32 v[94:95], v[0:1], v[80:81]
	v_add_f32_e32 v92, v90, v91
	v_pk_fma_f32 v[94:95], v[2:3], v[82:83], v[94:95]
	ds_read_b128 v[44:47], v67 offset:18816
	v_add_f32_dpp v92, v92, v92 quad_perm:[1,0,3,2] row_mask:0xf bank_mask:0xf bound_ctrl:1
	ds_read_b128 v[52:55], v67 offset:19328
	ds_read_b128 v[56:59], v67 offset:19584
	v_add_f32_dpp v92, v92, v92 quad_perm:[2,3,0,1] row_mask:0xf bank_mask:0xf bound_ctrl:1
	ds_read_b128 v[48:51], v67 offset:19072
	ds_read_b128 v[80:83], v67 offset:19840
	v_add_f32_dpp v92, v92, v92 row_half_mirror row_mask:0xf bank_mask:0xf bound_ctrl:1
	ds_read_b32 v78, v85 offset:20096
	v_pk_fma_f32 v[88:89], v[2:3], v[18:19], v[88:89]
	v_add_f32_dpp v92, v92, v92 row_mirror row_mask:0xf bank_mask:0xf bound_ctrl:1
	v_add_f32_e32 v99, v94, v95
	v_cndmask_b32_e64 v100, v98, v96, s[6:7]
	v_pk_fma_f32 v[0:1], v[8:9], v[92:93], v[86:87] op_sel_hi:[1,0,1]
	v_pk_fma_f32 v[2:3], v[10:11], v[92:93], v[88:89] op_sel_hi:[1,0,1]
	v_cndmask_b32_e64 v101, v96, v98, s[6:7]
	v_cndmask_b32_e64 v102, v99, v97, s[6:7]
	v_cndmask_b32_e64 v103, v97, v99, s[6:7]
	s_waitcnt lgkmcnt(6)
	v_pk_mul_f32 v[86:87], v[32:33], v[76:77] op_sel_hi:[1,0]
	v_pk_mul_f32 v[90:91], v[0:1], v[24:25]
	v_pk_mul_f32 v[88:89], v[34:35], v[76:77] op_sel_hi:[1,0]
	v_pk_fma_f32 v[90:91], v[2:3], v[26:27], v[90:91]
	v_pk_fma_f32 v[86:87], v[0:1], v[36:37], v[86:87]
	v_pk_mul_f32 v[94:95], v[0:1], v[20:21]
	v_add_f32_e32 v92, v90, v91
	v_pk_fma_f32 v[94:95], v[2:3], v[22:23], v[94:95]
	ds_read_b128 v[4:7], v67 offset:20160
	v_add_f32_dpp v92, v92, v92 quad_perm:[1,0,3,2] row_mask:0xf bank_mask:0xf bound_ctrl:1
	ds_read_b128 v[12:15], v67 offset:20672
	ds_read_b128 v[16:19], v67 offset:20928
	v_add_f32_dpp v92, v92, v92 quad_perm:[2,3,0,1] row_mask:0xf bank_mask:0xf bound_ctrl:1
	ds_read_b128 v[8:11], v67 offset:20416
	ds_read_b128 v[20:23], v67 offset:21184
	v_add_f32_dpp v92, v92, v92 row_half_mirror row_mask:0xf bank_mask:0xf bound_ctrl:1
	ds_read_b32 v74, v85 offset:21440
	v_pk_fma_f32 v[88:89], v[2:3], v[38:39], v[88:89]
	v_add_f32_dpp v92, v92, v92 row_mirror row_mask:0xf bank_mask:0xf bound_ctrl:1
	v_add_f32_e32 v96, v94, v95
	v_add_f32_dpp v100, v101, v100 quad_perm:[1,0,3,2] row_mask:0xf bank_mask:0xf bound_ctrl:1
	v_pk_fma_f32 v[0:1], v[28:29], v[92:93], v[86:87] op_sel_hi:[1,0,1]
	v_pk_fma_f32 v[2:3], v[30:31], v[92:93], v[88:89] op_sel_hi:[1,0,1]
	v_add_f32_dpp v103, v103, v102 quad_perm:[1,0,3,2] row_mask:0xf bank_mask:0xf bound_ctrl:1
	v_cndmask_b32_e64 v104, v103, v100, s[8:9]
	v_cndmask_b32_e64 v105, v100, v103, s[8:9]
	s_waitcnt lgkmcnt(6)
	v_pk_mul_f32 v[86:87], v[52:53], v[78:79] op_sel_hi:[1,0]
	v_pk_mul_f32 v[90:91], v[0:1], v[44:45]
	v_pk_mul_f32 v[88:89], v[54:55], v[78:79] op_sel_hi:[1,0]
	v_pk_fma_f32 v[90:91], v[2:3], v[46:47], v[90:91]
	v_pk_fma_f32 v[86:87], v[0:1], v[56:57], v[86:87]
	v_pk_mul_f32 v[94:95], v[0:1], v[40:41]
	v_add_f32_e32 v92, v90, v91
	v_pk_fma_f32 v[94:95], v[2:3], v[42:43], v[94:95]
	ds_read_b128 v[24:27], v67 offset:21504
	v_add_f32_dpp v92, v92, v92 quad_perm:[1,0,3,2] row_mask:0xf bank_mask:0xf bound_ctrl:1
	ds_read_b128 v[32:35], v67 offset:22016
	ds_read_b128 v[36:39], v67 offset:22272
	v_add_f32_dpp v92, v92, v92 quad_perm:[2,3,0,1] row_mask:0xf bank_mask:0xf bound_ctrl:1
	ds_read_b128 v[28:31], v67 offset:21760
	ds_read_b128 v[40:43], v67 offset:22528
	v_add_f32_dpp v92, v92, v92 row_half_mirror row_mask:0xf bank_mask:0xf bound_ctrl:1
	ds_read_b32 v76, v85 offset:22784
	v_pk_fma_f32 v[88:89], v[2:3], v[58:59], v[88:89]
	v_add_f32_dpp v92, v92, v92 row_mirror row_mask:0xf bank_mask:0xf bound_ctrl:1
	v_add_f32_e32 v97, v94, v95
	v_add_f32_dpp v105, v105, v104 quad_perm:[2,3,0,1] row_mask:0xf bank_mask:0xf bound_ctrl:1
	v_pk_fma_f32 v[0:1], v[48:49], v[92:93], v[86:87] op_sel_hi:[1,0,1]
	v_pk_fma_f32 v[2:3], v[50:51], v[92:93], v[88:89] op_sel_hi:[1,0,1]
	v_add_f32_dpp v105, v105, v105 row_ror:4 row_mask:0xf bank_mask:0xf bound_ctrl:1
	s_waitcnt lgkmcnt(6)
	v_pk_mul_f32 v[86:87], v[12:13], v[74:75] op_sel_hi:[1,0]
	v_pk_mul_f32 v[90:91], v[0:1], v[4:5]
	v_pk_mul_f32 v[88:89], v[14:15], v[74:75] op_sel_hi:[1,0]
	v_pk_fma_f32 v[90:91], v[2:3], v[6:7], v[90:91]
	v_pk_fma_f32 v[86:87], v[0:1], v[16:17], v[86:87]
	v_pk_mul_f32 v[94:95], v[0:1], v[80:81]
	v_add_f32_e32 v92, v90, v91
	v_pk_fma_f32 v[94:95], v[2:3], v[82:83], v[94:95]
	ds_read_b128 v[44:47], v67 offset:22848
	v_add_f32_dpp v92, v92, v92 quad_perm:[1,0,3,2] row_mask:0xf bank_mask:0xf bound_ctrl:1
	ds_read_b128 v[52:55], v67 offset:23360
	ds_read_b128 v[56:59], v67 offset:23616
	v_add_f32_dpp v92, v92, v92 quad_perm:[2,3,0,1] row_mask:0xf bank_mask:0xf bound_ctrl:1
	ds_read_b128 v[48:51], v67 offset:23104
	ds_read_b128 v[80:83], v67 offset:23872
	v_add_f32_dpp v92, v92, v92 row_half_mirror row_mask:0xf bank_mask:0xf bound_ctrl:1
	ds_read_b32 v78, v85 offset:24128
	v_pk_fma_f32 v[88:89], v[2:3], v[18:19], v[88:89]
	v_add_f32_dpp v92, v92, v92 row_mirror row_mask:0xf bank_mask:0xf bound_ctrl:1
	v_add_f32_e32 v98, v94, v95
	v_mov_b32_dpp v106, v105 row_ror:8 row_mask:0xf bank_mask:0xf bound_ctrl:1
	v_pk_fma_f32 v[0:1], v[8:9], v[92:93], v[86:87] op_sel_hi:[1,0,1]
	v_pk_fma_f32 v[2:3], v[10:11], v[92:93], v[88:89] op_sel_hi:[1,0,1]
	v_add_f32_e32 v107, v105, v106
	v_cvt_pk_bf16_f32 v107, v107, v107
	s_and_saveexec_b64 s[16:17], s[4:5]
	global_store_short v[72:73], v107, off
	s_or_b64 exec, exec, s[16:17]
	v_lshl_add_u64 v[72:73], v[72:73], 0, s[14:15]
	s_waitcnt lgkmcnt(6)
	v_pk_mul_f32 v[86:87], v[32:33], v[76:77] op_sel_hi:[1,0]
	v_pk_mul_f32 v[90:91], v[0:1], v[24:25]
	v_pk_mul_f32 v[88:89], v[34:35], v[76:77] op_sel_hi:[1,0]
	v_pk_fma_f32 v[90:91], v[2:3], v[26:27], v[90:91]
	v_pk_fma_f32 v[86:87], v[0:1], v[36:37], v[86:87]
	v_pk_mul_f32 v[94:95], v[0:1], v[20:21]
	v_add_f32_e32 v92, v90, v91
	v_pk_fma_f32 v[94:95], v[2:3], v[22:23], v[94:95]
	ds_read_b128 v[4:7], v67 offset:24192
	v_add_f32_dpp v92, v92, v92 quad_perm:[1,0,3,2] row_mask:0xf bank_mask:0xf bound_ctrl:1
	ds_read_b128 v[12:15], v67 offset:24704
	ds_read_b128 v[16:19], v67 offset:24960
	v_add_f32_dpp v92, v92, v92 quad_perm:[2,3,0,1] row_mask:0xf bank_mask:0xf bound_ctrl:1
	ds_read_b128 v[8:11], v67 offset:24448
	ds_read_b128 v[20:23], v67 offset:25216
	v_add_f32_dpp v92, v92, v92 row_half_mirror row_mask:0xf bank_mask:0xf bound_ctrl:1
	ds_read_b32 v74, v85 offset:25472
	v_pk_fma_f32 v[88:89], v[2:3], v[38:39], v[88:89]
	v_add_f32_dpp v92, v92, v92 row_mirror row_mask:0xf bank_mask:0xf bound_ctrl:1
	v_add_f32_e32 v99, v94, v95
	v_cndmask_b32_e64 v100, v98, v96, s[6:7]
	v_pk_fma_f32 v[0:1], v[28:29], v[92:93], v[86:87] op_sel_hi:[1,0,1]
	v_pk_fma_f32 v[2:3], v[30:31], v[92:93], v[88:89] op_sel_hi:[1,0,1]
	v_cndmask_b32_e64 v101, v96, v98, s[6:7]
	v_cndmask_b32_e64 v102, v99, v97, s[6:7]
	v_cndmask_b32_e64 v103, v97, v99, s[6:7]
	s_waitcnt lgkmcnt(6)
	v_pk_mul_f32 v[86:87], v[52:53], v[78:79] op_sel_hi:[1,0]
	v_pk_mul_f32 v[90:91], v[0:1], v[44:45]
	v_pk_mul_f32 v[88:89], v[54:55], v[78:79] op_sel_hi:[1,0]
	v_pk_fma_f32 v[90:91], v[2:3], v[46:47], v[90:91]
	v_pk_fma_f32 v[86:87], v[0:1], v[56:57], v[86:87]
	v_pk_mul_f32 v[94:95], v[0:1], v[40:41]
	v_add_f32_e32 v92, v90, v91
	v_pk_fma_f32 v[94:95], v[2:3], v[42:43], v[94:95]
	ds_read_b128 v[24:27], v67 offset:25536
	v_add_f32_dpp v92, v92, v92 quad_perm:[1,0,3,2] row_mask:0xf bank_mask:0xf bound_ctrl:1
	ds_read_b128 v[32:35], v67 offset:26048
	ds_read_b128 v[36:39], v67 offset:26304
	v_add_f32_dpp v92, v92, v92 quad_perm:[2,3,0,1] row_mask:0xf bank_mask:0xf bound_ctrl:1
	ds_read_b128 v[28:31], v67 offset:25792
	ds_read_b128 v[40:43], v67 offset:26560
	v_add_f32_dpp v92, v92, v92 row_half_mirror row_mask:0xf bank_mask:0xf bound_ctrl:1
	ds_read_b32 v76, v85 offset:26816
	v_pk_fma_f32 v[88:89], v[2:3], v[58:59], v[88:89]
	v_add_f32_dpp v92, v92, v92 row_mirror row_mask:0xf bank_mask:0xf bound_ctrl:1
	v_add_f32_e32 v96, v94, v95
	v_add_f32_dpp v100, v101, v100 quad_perm:[1,0,3,2] row_mask:0xf bank_mask:0xf bound_ctrl:1
	v_pk_fma_f32 v[0:1], v[48:49], v[92:93], v[86:87] op_sel_hi:[1,0,1]
	v_pk_fma_f32 v[2:3], v[50:51], v[92:93], v[88:89] op_sel_hi:[1,0,1]
	v_add_f32_dpp v103, v103, v102 quad_perm:[1,0,3,2] row_mask:0xf bank_mask:0xf bound_ctrl:1
	v_cndmask_b32_e64 v104, v103, v100, s[8:9]
	v_cndmask_b32_e64 v105, v100, v103, s[8:9]
	s_waitcnt lgkmcnt(6)
	v_pk_mul_f32 v[86:87], v[12:13], v[74:75] op_sel_hi:[1,0]
	v_pk_mul_f32 v[90:91], v[0:1], v[4:5]
	v_pk_mul_f32 v[88:89], v[14:15], v[74:75] op_sel_hi:[1,0]
	v_pk_fma_f32 v[90:91], v[2:3], v[6:7], v[90:91]
	v_pk_fma_f32 v[86:87], v[0:1], v[16:17], v[86:87]
	v_pk_mul_f32 v[94:95], v[0:1], v[80:81]
	v_add_f32_e32 v92, v90, v91
	v_pk_fma_f32 v[94:95], v[2:3], v[82:83], v[94:95]
	ds_read_b128 v[44:47], v67 offset:26880
	v_add_f32_dpp v92, v92, v92 quad_perm:[1,0,3,2] row_mask:0xf bank_mask:0xf bound_ctrl:1
	ds_read_b128 v[52:55], v67 offset:27392
	ds_read_b128 v[56:59], v67 offset:27648
	v_add_f32_dpp v92, v92, v92 quad_perm:[2,3,0,1] row_mask:0xf bank_mask:0xf bound_ctrl:1
	ds_read_b128 v[48:51], v67 offset:27136
	ds_read_b128 v[80:83], v67 offset:27904
	v_add_f32_dpp v92, v92, v92 row_half_mirror row_mask:0xf bank_mask:0xf bound_ctrl:1
	ds_read_b32 v78, v85 offset:28160
	v_pk_fma_f32 v[88:89], v[2:3], v[18:19], v[88:89]
	v_add_f32_dpp v92, v92, v92 row_mirror row_mask:0xf bank_mask:0xf bound_ctrl:1
	v_add_f32_e32 v97, v94, v95
	v_add_f32_dpp v105, v105, v104 quad_perm:[2,3,0,1] row_mask:0xf bank_mask:0xf bound_ctrl:1
	v_pk_fma_f32 v[0:1], v[8:9], v[92:93], v[86:87] op_sel_hi:[1,0,1]
	v_pk_fma_f32 v[2:3], v[10:11], v[92:93], v[88:89] op_sel_hi:[1,0,1]
	v_add_f32_dpp v105, v105, v105 row_ror:4 row_mask:0xf bank_mask:0xf bound_ctrl:1
	s_waitcnt lgkmcnt(6)
	v_pk_mul_f32 v[86:87], v[32:33], v[76:77] op_sel_hi:[1,0]
	v_pk_mul_f32 v[90:91], v[0:1], v[24:25]
	v_pk_mul_f32 v[88:89], v[34:35], v[76:77] op_sel_hi:[1,0]
	v_pk_fma_f32 v[90:91], v[2:3], v[26:27], v[90:91]
	v_pk_fma_f32 v[86:87], v[0:1], v[36:37], v[86:87]
	v_pk_mul_f32 v[94:95], v[0:1], v[20:21]
	v_add_f32_e32 v92, v90, v91
	v_pk_fma_f32 v[94:95], v[2:3], v[22:23], v[94:95]
	ds_read_b128 v[4:7], v67 offset:28224
	v_add_f32_dpp v92, v92, v92 quad_perm:[1,0,3,2] row_mask:0xf bank_mask:0xf bound_ctrl:1
	ds_read_b128 v[12:15], v67 offset:28736
	ds_read_b128 v[16:19], v67 offset:28992
	v_add_f32_dpp v92, v92, v92 quad_perm:[2,3,0,1] row_mask:0xf bank_mask:0xf bound_ctrl:1
	ds_read_b128 v[8:11], v67 offset:28480
	ds_read_b128 v[20:23], v67 offset:29248
	v_add_f32_dpp v92, v92, v92 row_half_mirror row_mask:0xf bank_mask:0xf bound_ctrl:1
	ds_read_b32 v74, v85 offset:29504
	v_pk_fma_f32 v[88:89], v[2:3], v[38:39], v[88:89]
	v_add_f32_dpp v92, v92, v92 row_mirror row_mask:0xf bank_mask:0xf bound_ctrl:1
	v_add_f32_e32 v98, v94, v95
	v_mov_b32_dpp v106, v105 row_ror:8 row_mask:0xf bank_mask:0xf bound_ctrl:1
	v_pk_fma_f32 v[0:1], v[28:29], v[92:93], v[86:87] op_sel_hi:[1,0,1]
	v_pk_fma_f32 v[2:3], v[30:31], v[92:93], v[88:89] op_sel_hi:[1,0,1]
	v_add_f32_e32 v107, v105, v106
	v_cvt_pk_bf16_f32 v107, v107, v107
	s_and_saveexec_b64 s[16:17], s[4:5]
	global_store_short v[72:73], v107, off
	s_or_b64 exec, exec, s[16:17]
	v_lshl_add_u64 v[72:73], v[72:73], 0, s[14:15]
	s_waitcnt lgkmcnt(6)
	v_pk_mul_f32 v[86:87], v[52:53], v[78:79] op_sel_hi:[1,0]
	v_pk_mul_f32 v[90:91], v[0:1], v[44:45]
	v_pk_mul_f32 v[88:89], v[54:55], v[78:79] op_sel_hi:[1,0]
	v_pk_fma_f32 v[90:91], v[2:3], v[46:47], v[90:91]
	v_pk_fma_f32 v[86:87], v[0:1], v[56:57], v[86:87]
	v_pk_mul_f32 v[94:95], v[0:1], v[40:41]
	v_add_f32_e32 v92, v90, v91
	v_pk_fma_f32 v[94:95], v[2:3], v[42:43], v[94:95]
	ds_read_b128 v[24:27], v67 offset:29568
	v_add_f32_dpp v92, v92, v92 quad_perm:[1,0,3,2] row_mask:0xf bank_mask:0xf bound_ctrl:1
	ds_read_b128 v[32:35], v67 offset:30080
	ds_read_b128 v[36:39], v67 offset:30336
	v_add_f32_dpp v92, v92, v92 quad_perm:[2,3,0,1] row_mask:0xf bank_mask:0xf bound_ctrl:1
	ds_read_b128 v[28:31], v67 offset:29824
	ds_read_b128 v[40:43], v67 offset:30592
	v_add_f32_dpp v92, v92, v92 row_half_mirror row_mask:0xf bank_mask:0xf bound_ctrl:1
	ds_read_b32 v76, v85 offset:30848
	v_pk_fma_f32 v[88:89], v[2:3], v[58:59], v[88:89]
	v_add_f32_dpp v92, v92, v92 row_mirror row_mask:0xf bank_mask:0xf bound_ctrl:1
	v_add_f32_e32 v99, v94, v95
	v_cndmask_b32_e64 v100, v98, v96, s[6:7]
	v_pk_fma_f32 v[0:1], v[48:49], v[92:93], v[86:87] op_sel_hi:[1,0,1]
	v_pk_fma_f32 v[2:3], v[50:51], v[92:93], v[88:89] op_sel_hi:[1,0,1]
	v_cndmask_b32_e64 v101, v96, v98, s[6:7]
	v_cndmask_b32_e64 v102, v99, v97, s[6:7]
	v_cndmask_b32_e64 v103, v97, v99, s[6:7]
	s_waitcnt lgkmcnt(6)
	v_pk_mul_f32 v[86:87], v[12:13], v[74:75] op_sel_hi:[1,0]
	v_pk_mul_f32 v[90:91], v[0:1], v[4:5]
	v_pk_mul_f32 v[88:89], v[14:15], v[74:75] op_sel_hi:[1,0]
	v_pk_fma_f32 v[90:91], v[2:3], v[6:7], v[90:91]
	v_pk_fma_f32 v[86:87], v[0:1], v[16:17], v[86:87]
	v_pk_mul_f32 v[94:95], v[0:1], v[80:81]
	v_add_f32_e32 v92, v90, v91
	v_pk_fma_f32 v[94:95], v[2:3], v[82:83], v[94:95]
	ds_read_b128 v[44:47], v67 offset:30912
	v_add_f32_dpp v92, v92, v92 quad_perm:[1,0,3,2] row_mask:0xf bank_mask:0xf bound_ctrl:1
	ds_read_b128 v[52:55], v67 offset:31424
	ds_read_b128 v[56:59], v67 offset:31680
	v_add_f32_dpp v92, v92, v92 quad_perm:[2,3,0,1] row_mask:0xf bank_mask:0xf bound_ctrl:1
	ds_read_b128 v[48:51], v67 offset:31168
	ds_read_b128 v[80:83], v67 offset:31936
	v_add_f32_dpp v92, v92, v92 row_half_mirror row_mask:0xf bank_mask:0xf bound_ctrl:1
	ds_read_b32 v78, v85 offset:32192
	v_pk_fma_f32 v[88:89], v[2:3], v[18:19], v[88:89]
	v_add_f32_dpp v92, v92, v92 row_mirror row_mask:0xf bank_mask:0xf bound_ctrl:1
	v_add_f32_e32 v96, v94, v95
	v_add_f32_dpp v100, v101, v100 quad_perm:[1,0,3,2] row_mask:0xf bank_mask:0xf bound_ctrl:1
	v_pk_fma_f32 v[0:1], v[8:9], v[92:93], v[86:87] op_sel_hi:[1,0,1]
	v_pk_fma_f32 v[2:3], v[10:11], v[92:93], v[88:89] op_sel_hi:[1,0,1]
	v_add_f32_dpp v103, v103, v102 quad_perm:[1,0,3,2] row_mask:0xf bank_mask:0xf bound_ctrl:1
	v_cndmask_b32_e64 v104, v103, v100, s[8:9]
	v_cndmask_b32_e64 v105, v100, v103, s[8:9]
	s_waitcnt lgkmcnt(6)
	v_pk_mul_f32 v[86:87], v[32:33], v[76:77] op_sel_hi:[1,0]
	v_pk_mul_f32 v[90:91], v[0:1], v[24:25]
	v_pk_mul_f32 v[88:89], v[34:35], v[76:77] op_sel_hi:[1,0]
	v_pk_fma_f32 v[90:91], v[2:3], v[26:27], v[90:91]
	v_pk_fma_f32 v[86:87], v[0:1], v[36:37], v[86:87]
	v_pk_mul_f32 v[94:95], v[0:1], v[20:21]
	v_add_f32_e32 v92, v90, v91
	v_pk_fma_f32 v[94:95], v[2:3], v[22:23], v[94:95]
	ds_read_b128 v[4:7], v67 offset:32256
	v_add_f32_dpp v92, v92, v92 quad_perm:[1,0,3,2] row_mask:0xf bank_mask:0xf bound_ctrl:1
	ds_read_b128 v[12:15], v67 offset:32768
	ds_read_b128 v[16:19], v67 offset:33024
	v_add_f32_dpp v92, v92, v92 quad_perm:[2,3,0,1] row_mask:0xf bank_mask:0xf bound_ctrl:1
	ds_read_b128 v[8:11], v67 offset:32512
	ds_read_b128 v[20:23], v67 offset:33280
	v_add_f32_dpp v92, v92, v92 row_half_mirror row_mask:0xf bank_mask:0xf bound_ctrl:1
	ds_read_b32 v74, v85 offset:33536
	v_pk_fma_f32 v[88:89], v[2:3], v[38:39], v[88:89]
	v_add_f32_dpp v92, v92, v92 row_mirror row_mask:0xf bank_mask:0xf bound_ctrl:1
	v_add_f32_e32 v97, v94, v95
	v_add_f32_dpp v105, v105, v104 quad_perm:[2,3,0,1] row_mask:0xf bank_mask:0xf bound_ctrl:1
	v_pk_fma_f32 v[0:1], v[28:29], v[92:93], v[86:87] op_sel_hi:[1,0,1]
	v_pk_fma_f32 v[2:3], v[30:31], v[92:93], v[88:89] op_sel_hi:[1,0,1]
	v_add_f32_dpp v105, v105, v105 row_ror:4 row_mask:0xf bank_mask:0xf bound_ctrl:1
	s_waitcnt lgkmcnt(6)
	v_pk_mul_f32 v[86:87], v[52:53], v[78:79] op_sel_hi:[1,0]
	v_pk_mul_f32 v[90:91], v[0:1], v[44:45]
	v_pk_mul_f32 v[88:89], v[54:55], v[78:79] op_sel_hi:[1,0]
	v_pk_fma_f32 v[90:91], v[2:3], v[46:47], v[90:91]
	v_pk_fma_f32 v[86:87], v[0:1], v[56:57], v[86:87]
	v_pk_mul_f32 v[94:95], v[0:1], v[40:41]
	v_add_f32_e32 v92, v90, v91
	v_pk_fma_f32 v[94:95], v[2:3], v[42:43], v[94:95]
	ds_read_b128 v[24:27], v67 offset:33600
	v_add_f32_dpp v92, v92, v92 quad_perm:[1,0,3,2] row_mask:0xf bank_mask:0xf bound_ctrl:1
	ds_read_b128 v[32:35], v67 offset:34112
	ds_read_b128 v[36:39], v67 offset:34368
	v_add_f32_dpp v92, v92, v92 quad_perm:[2,3,0,1] row_mask:0xf bank_mask:0xf bound_ctrl:1
	ds_read_b128 v[28:31], v67 offset:33856
	ds_read_b128 v[40:43], v67 offset:34624
	v_add_f32_dpp v92, v92, v92 row_half_mirror row_mask:0xf bank_mask:0xf bound_ctrl:1
	ds_read_b32 v76, v85 offset:34880
	v_pk_fma_f32 v[88:89], v[2:3], v[58:59], v[88:89]
	v_add_f32_dpp v92, v92, v92 row_mirror row_mask:0xf bank_mask:0xf bound_ctrl:1
	v_add_f32_e32 v98, v94, v95
	v_mov_b32_dpp v106, v105 row_ror:8 row_mask:0xf bank_mask:0xf bound_ctrl:1
	v_pk_fma_f32 v[0:1], v[48:49], v[92:93], v[86:87] op_sel_hi:[1,0,1]
	v_pk_fma_f32 v[2:3], v[50:51], v[92:93], v[88:89] op_sel_hi:[1,0,1]
	v_add_f32_e32 v107, v105, v106
	v_cvt_pk_bf16_f32 v107, v107, v107
	s_and_saveexec_b64 s[16:17], s[4:5]
	global_store_short v[72:73], v107, off
	s_or_b64 exec, exec, s[16:17]
	v_lshl_add_u64 v[72:73], v[72:73], 0, s[14:15]
	s_waitcnt lgkmcnt(6)
	v_pk_mul_f32 v[86:87], v[12:13], v[74:75] op_sel_hi:[1,0]
	v_pk_mul_f32 v[90:91], v[0:1], v[4:5]
	v_pk_mul_f32 v[88:89], v[14:15], v[74:75] op_sel_hi:[1,0]
	v_pk_fma_f32 v[90:91], v[2:3], v[6:7], v[90:91]
	v_pk_fma_f32 v[86:87], v[0:1], v[16:17], v[86:87]
	v_pk_mul_f32 v[94:95], v[0:1], v[80:81]
	v_add_f32_e32 v92, v90, v91
	v_pk_fma_f32 v[94:95], v[2:3], v[82:83], v[94:95]
	ds_read_b128 v[44:47], v67 offset:34944
	v_add_f32_dpp v92, v92, v92 quad_perm:[1,0,3,2] row_mask:0xf bank_mask:0xf bound_ctrl:1
	ds_read_b128 v[52:55], v67 offset:35456
	ds_read_b128 v[56:59], v67 offset:35712
	v_add_f32_dpp v92, v92, v92 quad_perm:[2,3,0,1] row_mask:0xf bank_mask:0xf bound_ctrl:1
	ds_read_b128 v[48:51], v67 offset:35200
	ds_read_b128 v[80:83], v67 offset:35968
	v_add_f32_dpp v92, v92, v92 row_half_mirror row_mask:0xf bank_mask:0xf bound_ctrl:1
	ds_read_b32 v78, v85 offset:36224
	v_pk_fma_f32 v[88:89], v[2:3], v[18:19], v[88:89]
	v_add_f32_dpp v92, v92, v92 row_mirror row_mask:0xf bank_mask:0xf bound_ctrl:1
	v_add_f32_e32 v99, v94, v95
	v_cndmask_b32_e64 v100, v98, v96, s[6:7]
	v_pk_fma_f32 v[0:1], v[8:9], v[92:93], v[86:87] op_sel_hi:[1,0,1]
	v_pk_fma_f32 v[2:3], v[10:11], v[92:93], v[88:89] op_sel_hi:[1,0,1]
	v_cndmask_b32_e64 v101, v96, v98, s[6:7]
	v_cndmask_b32_e64 v102, v99, v97, s[6:7]
	v_cndmask_b32_e64 v103, v97, v99, s[6:7]
	s_waitcnt lgkmcnt(6)
	v_pk_mul_f32 v[86:87], v[32:33], v[76:77] op_sel_hi:[1,0]
	v_pk_mul_f32 v[90:91], v[0:1], v[24:25]
	v_pk_mul_f32 v[88:89], v[34:35], v[76:77] op_sel_hi:[1,0]
	v_pk_fma_f32 v[90:91], v[2:3], v[26:27], v[90:91]
	v_pk_fma_f32 v[86:87], v[0:1], v[36:37], v[86:87]
	v_pk_mul_f32 v[94:95], v[0:1], v[20:21]
	v_add_f32_e32 v92, v90, v91
	v_pk_fma_f32 v[94:95], v[2:3], v[22:23], v[94:95]
	ds_read_b128 v[4:7], v67 offset:36288
	v_add_f32_dpp v92, v92, v92 quad_perm:[1,0,3,2] row_mask:0xf bank_mask:0xf bound_ctrl:1
	ds_read_b128 v[12:15], v67 offset:36800
	ds_read_b128 v[16:19], v67 offset:37056
	v_add_f32_dpp v92, v92, v92 quad_perm:[2,3,0,1] row_mask:0xf bank_mask:0xf bound_ctrl:1
	ds_read_b128 v[8:11], v67 offset:36544
	ds_read_b128 v[20:23], v67 offset:37312
	v_add_f32_dpp v92, v92, v92 row_half_mirror row_mask:0xf bank_mask:0xf bound_ctrl:1
	ds_read_b32 v74, v85 offset:37568
	v_pk_fma_f32 v[88:89], v[2:3], v[38:39], v[88:89]
	v_add_f32_dpp v92, v92, v92 row_mirror row_mask:0xf bank_mask:0xf bound_ctrl:1
	v_add_f32_e32 v96, v94, v95
	v_add_f32_dpp v100, v101, v100 quad_perm:[1,0,3,2] row_mask:0xf bank_mask:0xf bound_ctrl:1
	v_pk_fma_f32 v[0:1], v[28:29], v[92:93], v[86:87] op_sel_hi:[1,0,1]
	v_pk_fma_f32 v[2:3], v[30:31], v[92:93], v[88:89] op_sel_hi:[1,0,1]
	v_add_f32_dpp v103, v103, v102 quad_perm:[1,0,3,2] row_mask:0xf bank_mask:0xf bound_ctrl:1
	v_cndmask_b32_e64 v104, v103, v100, s[8:9]
	v_cndmask_b32_e64 v105, v100, v103, s[8:9]
	s_waitcnt lgkmcnt(6)
	v_pk_mul_f32 v[86:87], v[52:53], v[78:79] op_sel_hi:[1,0]
	v_pk_mul_f32 v[90:91], v[0:1], v[44:45]
	v_pk_mul_f32 v[88:89], v[54:55], v[78:79] op_sel_hi:[1,0]
	v_pk_fma_f32 v[90:91], v[2:3], v[46:47], v[90:91]
	v_pk_fma_f32 v[86:87], v[0:1], v[56:57], v[86:87]
	v_pk_mul_f32 v[94:95], v[0:1], v[40:41]
	v_add_f32_e32 v92, v90, v91
	v_pk_fma_f32 v[94:95], v[2:3], v[42:43], v[94:95]
	ds_read_b128 v[24:27], v67 offset:37632
	v_add_f32_dpp v92, v92, v92 quad_perm:[1,0,3,2] row_mask:0xf bank_mask:0xf bound_ctrl:1
	ds_read_b128 v[32:35], v67 offset:38144
	ds_read_b128 v[36:39], v67 offset:38400
	v_add_f32_dpp v92, v92, v92 quad_perm:[2,3,0,1] row_mask:0xf bank_mask:0xf bound_ctrl:1
	ds_read_b128 v[28:31], v67 offset:37888
	ds_read_b128 v[40:43], v67 offset:38656
	v_add_f32_dpp v92, v92, v92 row_half_mirror row_mask:0xf bank_mask:0xf bound_ctrl:1
	ds_read_b32 v76, v85 offset:38912
	v_pk_fma_f32 v[88:89], v[2:3], v[58:59], v[88:89]
	v_add_f32_dpp v92, v92, v92 row_mirror row_mask:0xf bank_mask:0xf bound_ctrl:1
	v_add_f32_e32 v97, v94, v95
	v_add_f32_dpp v105, v105, v104 quad_perm:[2,3,0,1] row_mask:0xf bank_mask:0xf bound_ctrl:1
	v_pk_fma_f32 v[0:1], v[48:49], v[92:93], v[86:87] op_sel_hi:[1,0,1]
	v_pk_fma_f32 v[2:3], v[50:51], v[92:93], v[88:89] op_sel_hi:[1,0,1]
	v_add_f32_dpp v105, v105, v105 row_ror:4 row_mask:0xf bank_mask:0xf bound_ctrl:1
	s_waitcnt lgkmcnt(6)
	v_pk_mul_f32 v[86:87], v[12:13], v[74:75] op_sel_hi:[1,0]
	v_pk_mul_f32 v[90:91], v[0:1], v[4:5]
	v_pk_mul_f32 v[88:89], v[14:15], v[74:75] op_sel_hi:[1,0]
	v_pk_fma_f32 v[90:91], v[2:3], v[6:7], v[90:91]
	v_pk_fma_f32 v[86:87], v[0:1], v[16:17], v[86:87]
	v_pk_mul_f32 v[94:95], v[0:1], v[80:81]
	v_add_f32_e32 v92, v90, v91
	v_pk_fma_f32 v[94:95], v[2:3], v[82:83], v[94:95]
	ds_read_b128 v[44:47], v67 offset:38976
	v_add_f32_dpp v92, v92, v92 quad_perm:[1,0,3,2] row_mask:0xf bank_mask:0xf bound_ctrl:1
	ds_read_b128 v[52:55], v67 offset:39488
	ds_read_b128 v[56:59], v67 offset:39744
	v_add_f32_dpp v92, v92, v92 quad_perm:[2,3,0,1] row_mask:0xf bank_mask:0xf bound_ctrl:1
	ds_read_b128 v[48:51], v67 offset:39232
	ds_read_b128 v[80:83], v67 offset:40000
	v_add_f32_dpp v92, v92, v92 row_half_mirror row_mask:0xf bank_mask:0xf bound_ctrl:1
	ds_read_b32 v78, v85 offset:40256
	v_pk_fma_f32 v[88:89], v[2:3], v[18:19], v[88:89]
	v_add_f32_dpp v92, v92, v92 row_mirror row_mask:0xf bank_mask:0xf bound_ctrl:1
	v_add_f32_e32 v98, v94, v95
	v_mov_b32_dpp v106, v105 row_ror:8 row_mask:0xf bank_mask:0xf bound_ctrl:1
	v_pk_fma_f32 v[0:1], v[8:9], v[92:93], v[86:87] op_sel_hi:[1,0,1]
	v_pk_fma_f32 v[2:3], v[10:11], v[92:93], v[88:89] op_sel_hi:[1,0,1]
	v_add_f32_e32 v107, v105, v106
	v_cvt_pk_bf16_f32 v107, v107, v107
	s_and_saveexec_b64 s[16:17], s[4:5]
	global_store_short v[72:73], v107, off
	s_or_b64 exec, exec, s[16:17]
	v_lshl_add_u64 v[72:73], v[72:73], 0, s[14:15]
	s_waitcnt lgkmcnt(6)
	v_pk_mul_f32 v[86:87], v[32:33], v[76:77] op_sel_hi:[1,0]
	v_pk_mul_f32 v[90:91], v[0:1], v[24:25]
	v_pk_mul_f32 v[88:89], v[34:35], v[76:77] op_sel_hi:[1,0]
	v_pk_fma_f32 v[90:91], v[2:3], v[26:27], v[90:91]
	v_pk_fma_f32 v[86:87], v[0:1], v[36:37], v[86:87]
	v_pk_mul_f32 v[94:95], v[0:1], v[20:21]
	v_add_f32_e32 v92, v90, v91
	v_pk_fma_f32 v[94:95], v[2:3], v[22:23], v[94:95]
	ds_read_b128 v[4:7], v67 offset:40320
	v_add_f32_dpp v92, v92, v92 quad_perm:[1,0,3,2] row_mask:0xf bank_mask:0xf bound_ctrl:1
	ds_read_b128 v[12:15], v67 offset:40832
	ds_read_b128 v[16:19], v67 offset:41088
	v_add_f32_dpp v92, v92, v92 quad_perm:[2,3,0,1] row_mask:0xf bank_mask:0xf bound_ctrl:1
	ds_read_b128 v[8:11], v67 offset:40576
	ds_read_b128 v[20:23], v67 offset:41344
	v_add_f32_dpp v92, v92, v92 row_half_mirror row_mask:0xf bank_mask:0xf bound_ctrl:1
	ds_read_b32 v74, v85 offset:41600
	v_pk_fma_f32 v[88:89], v[2:3], v[38:39], v[88:89]
	v_add_f32_dpp v92, v92, v92 row_mirror row_mask:0xf bank_mask:0xf bound_ctrl:1
	v_add_f32_e32 v99, v94, v95
	v_cndmask_b32_e64 v100, v98, v96, s[6:7]
	v_pk_fma_f32 v[0:1], v[28:29], v[92:93], v[86:87] op_sel_hi:[1,0,1]
	v_pk_fma_f32 v[2:3], v[30:31], v[92:93], v[88:89] op_sel_hi:[1,0,1]
	v_cndmask_b32_e64 v101, v96, v98, s[6:7]
	v_cndmask_b32_e64 v102, v99, v97, s[6:7]
	v_cndmask_b32_e64 v103, v97, v99, s[6:7]
	s_waitcnt lgkmcnt(6)
	v_pk_mul_f32 v[86:87], v[52:53], v[78:79] op_sel_hi:[1,0]
	v_pk_mul_f32 v[90:91], v[0:1], v[44:45]
	v_pk_mul_f32 v[88:89], v[54:55], v[78:79] op_sel_hi:[1,0]
	v_pk_fma_f32 v[90:91], v[2:3], v[46:47], v[90:91]
	v_pk_fma_f32 v[86:87], v[0:1], v[56:57], v[86:87]
	v_pk_mul_f32 v[94:95], v[0:1], v[40:41]
	v_add_f32_e32 v92, v90, v91
	v_pk_fma_f32 v[94:95], v[2:3], v[42:43], v[94:95]
	ds_read_b128 v[24:27], v67 offset:41664
	v_add_f32_dpp v92, v92, v92 quad_perm:[1,0,3,2] row_mask:0xf bank_mask:0xf bound_ctrl:1
	ds_read_b128 v[32:35], v67 offset:42176
	ds_read_b128 v[36:39], v67 offset:42432
	v_add_f32_dpp v92, v92, v92 quad_perm:[2,3,0,1] row_mask:0xf bank_mask:0xf bound_ctrl:1
	ds_read_b128 v[28:31], v67 offset:41920
	ds_read_b128 v[40:43], v67 offset:42688
	v_add_f32_dpp v92, v92, v92 row_half_mirror row_mask:0xf bank_mask:0xf bound_ctrl:1
	ds_read_b32 v76, v85 offset:42944
	v_pk_fma_f32 v[88:89], v[2:3], v[58:59], v[88:89]
	v_add_f32_dpp v92, v92, v92 row_mirror row_mask:0xf bank_mask:0xf bound_ctrl:1
	v_add_f32_e32 v96, v94, v95
	v_add_f32_dpp v100, v101, v100 quad_perm:[1,0,3,2] row_mask:0xf bank_mask:0xf bound_ctrl:1
	v_pk_fma_f32 v[0:1], v[48:49], v[92:93], v[86:87] op_sel_hi:[1,0,1]
	v_pk_fma_f32 v[2:3], v[50:51], v[92:93], v[88:89] op_sel_hi:[1,0,1]
	v_add_f32_dpp v103, v103, v102 quad_perm:[1,0,3,2] row_mask:0xf bank_mask:0xf bound_ctrl:1
	v_cndmask_b32_e64 v104, v103, v100, s[8:9]
	v_cndmask_b32_e64 v105, v100, v103, s[8:9]
	s_waitcnt lgkmcnt(6)
	v_pk_mul_f32 v[86:87], v[12:13], v[74:75] op_sel_hi:[1,0]
	v_pk_mul_f32 v[90:91], v[0:1], v[4:5]
	v_pk_mul_f32 v[88:89], v[14:15], v[74:75] op_sel_hi:[1,0]
	v_pk_fma_f32 v[90:91], v[2:3], v[6:7], v[90:91]
	v_pk_fma_f32 v[86:87], v[0:1], v[16:17], v[86:87]
	v_pk_mul_f32 v[94:95], v[0:1], v[80:81]
	v_add_f32_e32 v92, v90, v91
	v_pk_fma_f32 v[94:95], v[2:3], v[82:83], v[94:95]
	s_nop 0
	v_add_f32_dpp v92, v92, v92 quad_perm:[1,0,3,2] row_mask:0xf bank_mask:0xf bound_ctrl:1
	s_nop 1
	v_add_f32_dpp v92, v92, v92 quad_perm:[2,3,0,1] row_mask:0xf bank_mask:0xf bound_ctrl:1
	s_nop 1
	v_add_f32_dpp v92, v92, v92 row_half_mirror row_mask:0xf bank_mask:0xf bound_ctrl:1
	v_pk_fma_f32 v[88:89], v[2:3], v[18:19], v[88:89]
	s_nop 0
	v_add_f32_dpp v92, v92, v92 row_mirror row_mask:0xf bank_mask:0xf bound_ctrl:1
	v_add_f32_e32 v97, v94, v95
	v_add_f32_dpp v105, v105, v104 quad_perm:[2,3,0,1] row_mask:0xf bank_mask:0xf bound_ctrl:1
	v_pk_fma_f32 v[0:1], v[8:9], v[92:93], v[86:87] op_sel_hi:[1,0,1]
	v_pk_fma_f32 v[2:3], v[10:11], v[92:93], v[88:89] op_sel_hi:[1,0,1]
	v_add_f32_dpp v105, v105, v105 row_ror:4 row_mask:0xf bank_mask:0xf bound_ctrl:1
	s_waitcnt lgkmcnt(0)
	v_pk_mul_f32 v[86:87], v[32:33], v[76:77] op_sel_hi:[1,0]
	v_pk_mul_f32 v[90:91], v[0:1], v[24:25]
	v_pk_mul_f32 v[88:89], v[34:35], v[76:77] op_sel_hi:[1,0]
	v_pk_fma_f32 v[90:91], v[2:3], v[26:27], v[90:91]
	v_pk_fma_f32 v[86:87], v[0:1], v[36:37], v[86:87]
	v_pk_mul_f32 v[94:95], v[0:1], v[20:21]
	v_add_f32_e32 v92, v90, v91
	v_pk_fma_f32 v[94:95], v[2:3], v[22:23], v[94:95]
	s_nop 0
	v_add_f32_dpp v92, v92, v92 quad_perm:[1,0,3,2] row_mask:0xf bank_mask:0xf bound_ctrl:1
	s_nop 1
	v_add_f32_dpp v92, v92, v92 quad_perm:[2,3,0,1] row_mask:0xf bank_mask:0xf bound_ctrl:1
	s_nop 1
	v_add_f32_dpp v92, v92, v92 row_half_mirror row_mask:0xf bank_mask:0xf bound_ctrl:1
	v_pk_fma_f32 v[88:89], v[2:3], v[38:39], v[88:89]
	s_nop 0
	v_add_f32_dpp v92, v92, v92 row_mirror row_mask:0xf bank_mask:0xf bound_ctrl:1
	v_add_f32_e32 v98, v94, v95
	v_mov_b32_dpp v106, v105 row_ror:8 row_mask:0xf bank_mask:0xf bound_ctrl:1
	v_pk_fma_f32 v[0:1], v[28:29], v[92:93], v[86:87] op_sel_hi:[1,0,1]
	v_pk_fma_f32 v[2:3], v[30:31], v[92:93], v[88:89] op_sel_hi:[1,0,1]
	v_add_f32_e32 v107, v105, v106
	v_cvt_pk_bf16_f32 v107, v107, v107
	s_and_saveexec_b64 s[16:17], s[4:5]
	global_store_short v[72:73], v107, off
	s_or_b64 exec, exec, s[16:17]
	v_lshl_add_u64 v[72:73], v[72:73], 0, s[14:15]
	v_pk_mul_f32 v[94:95], v[0:1], v[40:41]
	v_pk_fma_f32 v[94:95], v[2:3], v[42:43], v[94:95]
	v_add_f32_e32 v99, v94, v95
	v_cndmask_b32_e64 v100, v98, v96, s[6:7]
	v_cndmask_b32_e64 v101, v96, v98, s[6:7]
	v_cndmask_b32_e64 v102, v99, v97, s[6:7]
	v_cndmask_b32_e64 v103, v97, v99, s[6:7]
	v_add_f32_dpp v100, v101, v100 quad_perm:[1,0,3,2] row_mask:0xf bank_mask:0xf bound_ctrl:1
	s_nop 0
	v_add_f32_dpp v103, v103, v102 quad_perm:[1,0,3,2] row_mask:0xf bank_mask:0xf bound_ctrl:1
	v_cndmask_b32_e64 v104, v103, v100, s[8:9]
	v_cndmask_b32_e64 v105, v100, v103, s[8:9]
	s_nop 1
	v_add_f32_dpp v105, v105, v104 quad_perm:[2,3,0,1] row_mask:0xf bank_mask:0xf bound_ctrl:1
	s_nop 1
	v_add_f32_dpp v105, v105, v105 row_ror:4 row_mask:0xf bank_mask:0xf bound_ctrl:1
	s_nop 1
	v_mov_b32_dpp v106, v105 row_ror:8 row_mask:0xf bank_mask:0xf bound_ctrl:1
	v_add_f32_e32 v107, v105, v106
	v_cvt_pk_bf16_f32 v107, v107, v107
	s_and_saveexec_b64 s[16:17], s[4:5]
	global_store_short v[72:73], v107, off
	s_or_b64 exec, exec, s[16:17]
	v_lshl_add_u64 v[72:73], v[72:73], 0, s[14:15]
	s_branch .LBB0_1334

.LBB0_1763:
	s_ashr_i32 s3, s2, 31
	s_lshl_b64 s[16:17], s[2:3], 11
	v_lshl_add_u64 v[14:15], v[0:1], 0, s[16:17]
	global_load_ushort v13, v[14:15], off
	v_lshl_add_u64 v[14:15], v[2:3], 0, s[16:17]
	global_load_ushort v17, v[14:15], off
	v_lshl_add_u64 v[14:15], v[6:7], 0, s[16:17]
	s_lshl_b64 s[2:3], s[2:3], 6
	global_load_ushort v16, v[14:15], off
	v_lshl_add_u64 v[14:15], v[8:9], 0, s[16:17]
	s_add_u32 s2, s65, s2
	global_load_ushort v18, v[14:15], off
	v_lshl_add_u64 v[14:15], v[4:5], 0, s[16:17]
	s_addc_u32 s3, s66, s3
	global_load_ushort v15, v[14:15], off
	v_cvt_f32_f16_e32 v100, v96
	global_load_dword v14, v153, s[2:3]
	v_cvt_f32_f16_e32 v102, v99
	s_add_i32 s80, s61, 32
	s_and_b32 s2, s80, 32
	v_mul_f32_e32 v85, v10, v85
	s_add_i32 s2, s2, s75
	v_mul_f32_e32 v103, v85, v100
	v_add_f32_e32 v85, -1.0, v102
	s_mulk_i32 s2, 0x540
	v_fma_f32 v85, v12, v85, 1.0
	v_mul_f32_e32 v100, v85, v100
	v_add_u32_e32 v85, s2, v84
	v_mul_f32_e64 v102, v103, -v102
	ds_write2st64_b32 v85, v103, v102 offset1:1
	v_cvt_f32_f16_e32 v102, v97
	v_cvt_f32_f16_e32 v101, v95
	v_sub_f32_e32 v102, 1.0, v102
	ds_write2st64_b32 v85, v100, v102 offset0:2 offset1:3
	ds_write_b32 v85, v101 offset:1024
	s_and_saveexec_b64 s[2:3], s[10:11]
	v_cvt_f32_f16_e32 v102, v98
	ds_write_b32 v85, v102 offset:1280
	s_or_b64 exec, exec, s[2:3]
	s_add_i32 s60, s60, 1
	s_lshl_b32 s82, s60, 5
	s_and_b64 vcc, exec, s[14:15]
	s_add_i32 s82, s82, s75
	s_and_b32 s2, s55, 3
	s_cmp_lg_u32 s2, 0
	s_cbranch_scc1 .LBB0_1780
	v_mul_f32_e32 v100, v100, v101
	v_mul_f32_e32 v101, v11, v100
	s_nop 1
	v_mov_b32_dpp v101, v101 quad_perm:[1,0,3,2] row_mask:0xf bank_mask:0xf bound_ctrl:1
	v_fmac_f32_e32 v101, v11, v100
	s_nop 1
	v_add_f32_dpp v100, v101, v101 quad_perm:[2,3,0,1] row_mask:0xf bank_mask:0xf bound_ctrl:1
	s_nop 1
	v_add_f32_dpp v100, v100, v100 row_half_mirror row_mask:0xf bank_mask:0xf bound_ctrl:1
	s_nop 1
	v_add_f32_dpp v100, v100, v100 row_mirror row_mask:0xf bank_mask:0xf bound_ctrl:1
	v_mov_b32_e32 v101, v100
	s_nop 1
	v_permlane16_swap_b32 v100, v101
	s_nop 1
	s_nop 0
	v_add_f32_e32 v100, v100, v101
	v_mov_b32_e32 v101, v100
	s_nop 1
	v_permlane32_swap_b32 v100, v101
	s_nop 1
	s_and_saveexec_b64 s[2:3], s[12:13]
	s_cbranch_execz .LBB0_1779
	s_cmpk_gt_i32 s67, 0xff
	s_mov_b64 s[58:59], -1
	s_cbranch_scc0 .LBB0_1773
	s_andn2_b64 vcc, exec, s[0:1]
	s_cbranch_vccnz .LBB0_1770
	s_sub_i32 s16, s44, s82
	s_mov_b64 s[58:59], 0

.LBB0_1780:
	v_cvt_f32_f16_sdwa v96, v96 dst_sel:DWORD dst_unused:UNUSED_PAD src0_sel:WORD_1
	v_cvt_f32_f16_sdwa v99, v99 dst_sel:DWORD dst_unused:UNUSED_PAD src0_sel:WORD_1
	v_cvt_f32_f16_sdwa v97, v97 dst_sel:DWORD dst_unused:UNUSED_PAD src0_sel:WORD_1
	v_mul_f32_e32 v82, v10, v82
	v_cvt_f32_f16_sdwa v95, v95 dst_sel:DWORD dst_unused:UNUSED_PAD src0_sel:WORD_1
	v_mul_f32_e32 v100, v82, v96
	v_add_f32_e32 v82, -1.0, v99
	v_fma_f32 v82, v12, v82, 1.0
	v_mul_f32_e32 v96, v82, v96
	v_mul_f32_e64 v99, v100, -v99
	v_add_u32_e32 v82, 64, v85
	v_sub_f32_e32 v97, 1.0, v97
	ds_write2st64_b32 v82, v100, v99 offset0:5 offset1:6
	ds_write2st64_b32 v82, v96, v97 offset0:7 offset1:8
	ds_write_b32 v85, v95 offset:2368
	s_and_saveexec_b64 s[2:3], s[10:11]
	v_cvt_f32_f16_sdwa v97, v98 dst_sel:DWORD dst_unused:UNUSED_PAD src0_sel:WORD_1
	ds_write_b32 v85, v97 offset:2624
	s_or_b64 exec, exec, s[2:3]
	s_and_b64 vcc, exec, s[14:15]
	s_and_b32 s2, s55, 3
	s_cmp_lg_u32 s2, 1
	s_cbranch_scc1 .LBB0_1797
	v_mul_f32_e32 v95, v96, v95
	v_mul_f32_e32 v96, v11, v95
	s_nop 1
	v_mov_b32_dpp v96, v96 quad_perm:[1,0,3,2] row_mask:0xf bank_mask:0xf bound_ctrl:1
	v_fmac_f32_e32 v96, v11, v95
	s_nop 1
	v_add_f32_dpp v95, v96, v96 quad_perm:[2,3,0,1] row_mask:0xf bank_mask:0xf bound_ctrl:1
	s_nop 1
	v_add_f32_dpp v95, v95, v95 row_half_mirror row_mask:0xf bank_mask:0xf bound_ctrl:1
	s_nop 1
	v_add_f32_dpp v95, v95, v95 row_mirror row_mask:0xf bank_mask:0xf bound_ctrl:1
	v_mov_b32_e32 v96, v95
	s_nop 1
	v_permlane16_swap_b32 v95, v96
	s_nop 1
	s_nop 0
	v_add_f32_e32 v95, v95, v96
	v_mov_b32_e32 v96, v95
	s_nop 1
	v_permlane32_swap_b32 v95, v96
	s_nop 1
	s_and_saveexec_b64 s[2:3], s[12:13]
	s_cbranch_execz .LBB0_1796
	s_or_b32 s17, s82, 1
	s_add_i32 s16, s67, 1
	s_cmpk_lt_i32 s16, 0x100
	s_mov_b64 s[58:59], -1
	s_cbranch_scc1 .LBB0_1790
	s_andn2_b64 vcc, exec, s[0:1]
	s_cbranch_vccnz .LBB0_1787
	s_sub_i32 s16, s44, s17
	s_mov_b64 s[58:59], 0

.LBB0_1797:
	v_cvt_f32_f16_e32 v95, v91
	v_cvt_f32_f16_e32 v97, v94
	v_mul_f32_e32 v81, v10, v81
	v_cvt_f32_f16_e32 v96, v90
	v_mul_f32_e32 v98, v81, v95
	v_add_f32_e32 v81, -1.0, v97
	v_fma_f32 v81, v12, v81, 1.0
	v_mul_f32_e32 v95, v81, v95
	v_mul_f32_e64 v97, v98, -v97
	v_add_u32_e32 v81, 0x80, v85
	ds_write2st64_b32 v81, v98, v97 offset0:10 offset1:11
	v_cvt_f32_f16_e32 v97, v92
	v_sub_f32_e32 v97, 1.0, v97
	ds_write2st64_b32 v81, v95, v97 offset0:12 offset1:13
	ds_write_b32 v85, v96 offset:3712
	s_and_saveexec_b64 s[2:3], s[10:11]
	v_cvt_f32_f16_e32 v97, v93
	ds_write_b32 v85, v97 offset:3968
	s_or_b64 exec, exec, s[2:3]
	s_and_b64 vcc, exec, s[14:15]
	s_and_b32 s2, s55, 3
	s_cmp_lg_u32 s2, 2
	s_cbranch_scc1 .LBB0_1814
	v_mul_f32_e32 v95, v95, v96
	v_mul_f32_e32 v96, v11, v95
	s_nop 1
	v_mov_b32_dpp v96, v96 quad_perm:[1,0,3,2] row_mask:0xf bank_mask:0xf bound_ctrl:1
	v_fmac_f32_e32 v96, v11, v95
	s_nop 1
	v_add_f32_dpp v95, v96, v96 quad_perm:[2,3,0,1] row_mask:0xf bank_mask:0xf bound_ctrl:1
	s_nop 1
	v_add_f32_dpp v95, v95, v95 row_half_mirror row_mask:0xf bank_mask:0xf bound_ctrl:1
	s_nop 1
	v_add_f32_dpp v95, v95, v95 row_mirror row_mask:0xf bank_mask:0xf bound_ctrl:1
	v_mov_b32_e32 v96, v95
	s_nop 1
	v_permlane16_swap_b32 v96, v95
	s_nop 1
	s_nop 0
	v_add_f32_e32 v95, v96, v95
	v_mov_b32_e32 v96, v95
	s_nop 1
	v_permlane32_swap_b32 v96, v95
	s_nop 1
	s_and_saveexec_b64 s[2:3], s[12:13]
	s_cbranch_execz .LBB0_1813
	s_or_b32 s17, s82, 2
	s_add_i32 s16, s67, 2
	s_cmpk_lt_i32 s16, 0x100
	s_mov_b64 s[58:59], -1
	s_cbranch_scc1 .LBB0_1807
	s_andn2_b64 vcc, exec, s[0:1]
	s_cbranch_vccnz .LBB0_1804
	s_sub_i32 s16, s44, s17
	s_mov_b64 s[58:59], 0

.LBB0_1814:
	v_cvt_f32_f16_sdwa v91, v91 dst_sel:DWORD dst_unused:UNUSED_PAD src0_sel:WORD_1
	v_cvt_f32_f16_sdwa v94, v94 dst_sel:DWORD dst_unused:UNUSED_PAD src0_sel:WORD_1
	v_cvt_f32_f16_sdwa v92, v92 dst_sel:DWORD dst_unused:UNUSED_PAD src0_sel:WORD_1
	v_mul_f32_e32 v80, v10, v80
	v_cvt_f32_f16_sdwa v90, v90 dst_sel:DWORD dst_unused:UNUSED_PAD src0_sel:WORD_1
	v_mul_f32_e32 v95, v80, v91
	v_add_f32_e32 v80, -1.0, v94
	v_fma_f32 v80, v12, v80, 1.0
	v_mul_f32_e32 v91, v80, v91
	v_mul_f32_e64 v94, v95, -v94
	v_add_u32_e32 v80, 0xc0, v85
	v_sub_f32_e32 v92, 1.0, v92
	ds_write2st64_b32 v80, v95, v94 offset0:15 offset1:16
	ds_write2st64_b32 v80, v91, v92 offset0:17 offset1:18
	ds_write_b32 v85, v90 offset:5056
	s_and_saveexec_b64 s[2:3], s[10:11]
	v_cvt_f32_f16_sdwa v92, v93 dst_sel:DWORD dst_unused:UNUSED_PAD src0_sel:WORD_1
	ds_write_b32 v85, v92 offset:5312
	s_or_b64 exec, exec, s[2:3]
	s_and_b64 vcc, exec, s[14:15]
	s_and_b32 s2, s55, 3
	s_cmp_lg_u32 s2, 3
	s_cbranch_scc1 .LBB0_1831
	v_mul_f32_e32 v90, v91, v90
	v_mul_f32_e32 v91, v11, v90
	s_nop 1
	v_mov_b32_dpp v91, v91 quad_perm:[1,0,3,2] row_mask:0xf bank_mask:0xf bound_ctrl:1
	v_fmac_f32_e32 v91, v11, v90
	s_nop 1
	v_add_f32_dpp v90, v91, v91 quad_perm:[2,3,0,1] row_mask:0xf bank_mask:0xf bound_ctrl:1
	s_nop 1
	v_add_f32_dpp v90, v90, v90 row_half_mirror row_mask:0xf bank_mask:0xf bound_ctrl:1
	s_nop 1
	v_add_f32_dpp v90, v90, v90 row_mirror row_mask:0xf bank_mask:0xf bound_ctrl:1
	v_mov_b32_e32 v91, v90
	s_nop 1
	v_permlane16_swap_b32 v90, v91
	s_nop 1
	s_nop 0
	v_add_f32_e32 v90, v90, v91
	v_mov_b32_e32 v91, v90
	s_nop 1
	v_permlane32_swap_b32 v90, v91
	s_nop 1
	s_and_saveexec_b64 s[2:3], s[12:13]
	s_cbranch_execz .LBB0_1830
	s_or_b32 s17, s82, 3
	s_add_i32 s16, s67, 3
	s_cmpk_lt_i32 s16, 0x100
	s_mov_b64 s[58:59], -1
	s_cbranch_scc1 .LBB0_1824
	s_andn2_b64 vcc, exec, s[0:1]
	s_cbranch_vccnz .LBB0_1821
	s_sub_i32 s16, s44, s17
	s_mov_b64 s[58:59], 0

.LBB0_1831:
	v_cvt_f32_f16_e32 v90, v86
	v_cvt_f32_f16_e32 v91, v89
	v_mul_f32_e32 v76, v10, v76
	v_mul_f32_e32 v92, v76, v90
	v_add_f32_e32 v76, -1.0, v91
	v_mul_f32_e64 v91, v92, -v91
	v_fma_f32 v76, v12, v76, 1.0
	ds_write2st64_b32 v85, v92, v91 offset0:21 offset1:22
	v_cvt_f32_f16_e32 v91, v87
	v_mul_f32_e32 v76, v76, v90
	v_cvt_f32_f16_e32 v90, v83
	v_sub_f32_e32 v91, 1.0, v91
	ds_write2st64_b32 v85, v76, v91 offset0:23 offset1:24
	ds_write_b32 v85, v90 offset:6400
	s_and_saveexec_b64 s[2:3], s[10:11]
	v_cvt_f32_f16_e32 v91, v88
	ds_write_b32 v85, v91 offset:6656
	s_or_b64 exec, exec, s[2:3]
	s_and_b64 vcc, exec, s[14:15]
	s_and_b32 s2, s55, 3
	s_cmp_lg_u32 s2, 0
	s_cbranch_scc1 .LBB0_1848
	v_mul_f32_e32 v76, v76, v90
	v_mul_f32_e32 v90, v11, v76
	s_nop 1
	v_mov_b32_dpp v90, v90 quad_perm:[1,0,3,2] row_mask:0xf bank_mask:0xf bound_ctrl:1
	v_fmac_f32_e32 v90, v11, v76
	s_nop 1
	v_add_f32_dpp v76, v90, v90 quad_perm:[2,3,0,1] row_mask:0xf bank_mask:0xf bound_ctrl:1
	s_nop 1
	v_add_f32_dpp v76, v76, v76 row_half_mirror row_mask:0xf bank_mask:0xf bound_ctrl:1
	s_nop 1
	v_add_f32_dpp v76, v76, v76 row_mirror row_mask:0xf bank_mask:0xf bound_ctrl:1
	v_mov_b32_e32 v90, v76
	s_nop 1
	v_permlane16_swap_b32 v76, v90
	s_nop 1
	s_nop 0
	v_add_f32_e32 v76, v76, v90
	v_mov_b32_e32 v90, v76
	s_nop 1
	v_permlane32_swap_b32 v76, v90
	s_nop 1
	s_and_saveexec_b64 s[2:3], s[12:13]
	s_cbranch_execz .LBB0_1847
	s_or_b32 s17, s82, 4
	s_add_i32 s16, s67, 4
	s_cmpk_lt_i32 s16, 0x100
	s_mov_b64 s[58:59], -1
	s_cbranch_scc1 .LBB0_1841
	s_andn2_b64 vcc, exec, s[0:1]
	s_cbranch_vccnz .LBB0_1838
	s_sub_i32 s16, s44, s17
	s_mov_b64 s[58:59], 0

.LBB0_1848:
	v_cvt_f32_f16_sdwa v76, v86 dst_sel:DWORD dst_unused:UNUSED_PAD src0_sel:WORD_1
	v_cvt_f32_f16_sdwa v86, v89 dst_sel:DWORD dst_unused:UNUSED_PAD src0_sel:WORD_1
	v_mul_f32_e32 v57, v10, v57
	v_cvt_f32_f16_sdwa v87, v87 dst_sel:DWORD dst_unused:UNUSED_PAD src0_sel:WORD_1
	v_mul_f32_e32 v89, v57, v76
	v_add_f32_e32 v57, -1.0, v86
	v_fma_f32 v57, v12, v57, 1.0
	v_mul_f32_e32 v57, v57, v76
	v_cvt_f32_f16_sdwa v76, v83 dst_sel:DWORD dst_unused:UNUSED_PAD src0_sel:WORD_1
	v_mul_f32_e64 v83, v89, -v86
	ds_write2st64_b32 v82, v89, v83 offset0:26 offset1:27
	v_sub_f32_e32 v83, 1.0, v87
	ds_write2st64_b32 v82, v57, v83 offset0:28 offset1:29
	ds_write_b32 v85, v76 offset:7744
	s_and_saveexec_b64 s[2:3], s[10:11]
	v_cvt_f32_f16_sdwa v82, v88 dst_sel:DWORD dst_unused:UNUSED_PAD src0_sel:WORD_1
	ds_write_b32 v85, v82 offset:8000
	s_or_b64 exec, exec, s[2:3]
	s_and_b64 vcc, exec, s[14:15]
	s_and_b32 s2, s55, 3
	s_cmp_lg_u32 s2, 1
	s_cbranch_scc1 .LBB0_1865
	v_mul_f32_e32 v57, v57, v76
	v_mul_f32_e32 v76, v11, v57
	s_nop 1
	v_mov_b32_dpp v76, v76 quad_perm:[1,0,3,2] row_mask:0xf bank_mask:0xf bound_ctrl:1
	v_fmac_f32_e32 v76, v11, v57
	s_nop 1
	v_add_f32_dpp v57, v76, v76 quad_perm:[2,3,0,1] row_mask:0xf bank_mask:0xf bound_ctrl:1
	s_nop 1
	v_add_f32_dpp v57, v57, v57 row_half_mirror row_mask:0xf bank_mask:0xf bound_ctrl:1
	s_nop 1
	v_add_f32_dpp v57, v57, v57 row_mirror row_mask:0xf bank_mask:0xf bound_ctrl:1
	v_mov_b32_e32 v76, v57
	s_nop 1
	v_permlane16_swap_b32 v57, v76
	s_nop 1
	s_nop 0
	v_add_f32_e32 v57, v57, v76
	v_mov_b32_e32 v76, v57
	s_nop 1
	v_permlane32_swap_b32 v57, v76
	s_nop 1
	s_and_saveexec_b64 s[2:3], s[12:13]
	s_cbranch_execz .LBB0_1864
	s_or_b32 s17, s82, 5
	s_add_i32 s16, s67, 5
	s_cmpk_lt_i32 s16, 0x100
	s_mov_b64 s[58:59], -1
	s_cbranch_scc1 .LBB0_1858
	s_andn2_b64 vcc, exec, s[0:1]
	s_cbranch_vccnz .LBB0_1855
	s_sub_i32 s16, s44, s17
	s_mov_b64 s[58:59], 0

.LBB0_1865:
	v_cvt_f32_f16_e32 v57, v30
	v_cvt_f32_f16_e32 v76, v37
	v_mul_f32_e32 v47, v10, v47
	v_mul_f32_e32 v82, v47, v57
	v_add_f32_e32 v47, -1.0, v76
	v_mul_f32_e64 v76, v82, -v76
	v_fma_f32 v47, v12, v47, 1.0
	ds_write2st64_b32 v81, v82, v76 offset0:31 offset1:32
	v_cvt_f32_f16_e32 v76, v32
	v_mul_f32_e32 v47, v47, v57
	v_cvt_f32_f16_e32 v57, v25
	v_sub_f32_e32 v76, 1.0, v76
	ds_write2st64_b32 v81, v47, v76 offset0:33 offset1:34
	ds_write_b32 v85, v57 offset:9088
	s_and_saveexec_b64 s[2:3], s[10:11]
	v_cvt_f32_f16_e32 v76, v34
	ds_write_b32 v85, v76 offset:9344
	s_or_b64 exec, exec, s[2:3]
	s_and_b64 vcc, exec, s[14:15]
	s_and_b32 s2, s55, 3
	s_cmp_lg_u32 s2, 2
	s_cbranch_scc1 .LBB0_1882
	v_mul_f32_e32 v47, v47, v57
	v_mul_f32_e32 v57, v11, v47
	s_nop 1
	v_mov_b32_dpp v57, v57 quad_perm:[1,0,3,2] row_mask:0xf bank_mask:0xf bound_ctrl:1
	v_fmac_f32_e32 v57, v11, v47
	s_nop 1
	v_add_f32_dpp v47, v57, v57 quad_perm:[2,3,0,1] row_mask:0xf bank_mask:0xf bound_ctrl:1
	s_nop 1
	v_add_f32_dpp v47, v47, v47 row_half_mirror row_mask:0xf bank_mask:0xf bound_ctrl:1
	s_nop 1
	v_add_f32_dpp v47, v47, v47 row_mirror row_mask:0xf bank_mask:0xf bound_ctrl:1
	v_mov_b32_e32 v57, v47
	s_nop 1
	v_permlane16_swap_b32 v47, v57
	s_nop 1
	s_nop 0
	v_add_f32_e32 v47, v47, v57
	v_mov_b32_e32 v57, v47
	s_nop 1
	v_permlane32_swap_b32 v47, v57
	s_nop 1
	s_and_saveexec_b64 s[2:3], s[12:13]
	s_cbranch_execz .LBB0_1881
	s_or_b32 s17, s82, 6
	s_add_i32 s16, s67, 6
	s_cmpk_lt_i32 s16, 0x100
	s_mov_b64 s[58:59], -1
	s_cbranch_scc1 .LBB0_1875
	s_andn2_b64 vcc, exec, s[0:1]
	s_cbranch_vccnz .LBB0_1872
	s_sub_i32 s16, s44, s17
	s_mov_b64 s[58:59], 0

.LBB0_1882:
	v_cvt_f32_f16_sdwa v37, v37 dst_sel:DWORD dst_unused:UNUSED_PAD src0_sel:WORD_1
	v_cvt_f32_f16_sdwa v30, v30 dst_sel:DWORD dst_unused:UNUSED_PAD src0_sel:WORD_1
	v_cvt_f32_f16_sdwa v32, v32 dst_sel:DWORD dst_unused:UNUSED_PAD src0_sel:WORD_1
	v_cvt_f32_f16_sdwa v25, v25 dst_sel:DWORD dst_unused:UNUSED_PAD src0_sel:WORD_1
	s_waitcnt vmcnt(48)
	v_mul_f32_e32 v35, v10, v35
	v_add_f32_e32 v47, -1.0, v37
	v_mul_f32_e32 v35, v35, v30
	v_fma_f32 v47, v12, v47, 1.0
	v_mul_f32_e32 v30, v47, v30
	v_mul_f32_e64 v37, v35, -v37
	v_sub_f32_e32 v32, 1.0, v32
	ds_write2st64_b32 v80, v35, v37 offset0:36 offset1:37
	ds_write2st64_b32 v80, v30, v32 offset0:38 offset1:39
	ds_write_b32 v85, v25 offset:10432
	s_and_saveexec_b64 s[2:3], s[10:11]
	v_cvt_f32_f16_sdwa v32, v34 dst_sel:DWORD dst_unused:UNUSED_PAD src0_sel:WORD_1
	ds_write_b32 v85, v32 offset:10688
	s_or_b64 exec, exec, s[2:3]
	s_and_b64 vcc, exec, s[14:15]
	s_and_b32 s2, s55, 3
	s_cmp_lg_u32 s2, 3
	s_cbranch_scc1 .LBB0_1899
	v_mul_f32_e32 v25, v30, v25
	v_mul_f32_e32 v30, v11, v25
	s_nop 1
	v_mov_b32_dpp v30, v30 quad_perm:[1,0,3,2] row_mask:0xf bank_mask:0xf bound_ctrl:1
	v_fmac_f32_e32 v30, v11, v25
	s_nop 1
	v_add_f32_dpp v25, v30, v30 quad_perm:[2,3,0,1] row_mask:0xf bank_mask:0xf bound_ctrl:1
	s_nop 1
	v_add_f32_dpp v25, v25, v25 row_half_mirror row_mask:0xf bank_mask:0xf bound_ctrl:1
	s_nop 1
	v_add_f32_dpp v25, v25, v25 row_mirror row_mask:0xf bank_mask:0xf bound_ctrl:1
	v_mov_b32_e32 v30, v25
	s_nop 1
	v_permlane16_swap_b32 v30, v25
	s_nop 1
	s_nop 0
	v_add_f32_e32 v25, v30, v25
	v_mov_b32_e32 v30, v25
	s_nop 1
	v_permlane32_swap_b32 v30, v25
	s_nop 1
	s_and_saveexec_b64 s[2:3], s[12:13]
	s_cbranch_execz .LBB0_1898
	s_or_b32 s17, s82, 7
	s_add_i32 s67, s67, 7
	s_cmpk_lt_i32 s67, 0x100
	s_mov_b64 s[58:59], -1
	s_cbranch_scc1 .LBB0_1892
	s_andn2_b64 vcc, exec, s[0:1]
	s_cbranch_vccnz .LBB0_1889
	s_sub_i32 s16, s44, s17
	s_mov_b64 s[58:59], 0
